# attention: streamed exponentials in the pair jobs combined with store-aware counted waits in a unit's first job
# baseline (speedup 1.0000x reference)
.Latt_noedge_9:
	s_nop 1
	v_max3_f32 v186, v36, v37, v38
	v_max3_f32 v186, v186, v39, v40
	v_max3_f32 v186, v186, v41, v42
	v_max3_f32 v186, v186, v43, v44
	v_max3_f32 v186, v186, v45, v46
	v_max3_f32 v186, v186, v47, v48
	v_max3_f32 v186, v186, v49, v50
	v_max3_f32 v186, v186, v51, v52
	v_max3_f32 v186, v186, v53, v54
	v_max3_f32 v186, v186, v55, v56
	v_max3_f32 v186, v186, v57, v58
	v_max3_f32 v186, v186, v59, v60
	v_max3_f32 v186, v186, v61, v62
	v_max3_f32 v186, v186, v63, v64
	v_max3_f32 v186, v186, v65, v66
	v_max3_f32 v186, v186, v67, v68
	v_max3_f32 v186, v186, v69, v70
	v_max_f32_e32 v186, v186, v71
	v_mov_b32_e32 v146, v186
	s_nop 1
	v_permlane16_swap_b32_e32 v186, v146
	v_max_f32_e32 v186, v186, v146
	v_mov_b32_e32 v146, v186
	s_nop 1
	v_permlane32_swap_b32_e32 v186, v146
	v_max_f32_e32 v186, v186, v146
	s_waitcnt lgkmcnt(0)
	s_add_i32 s93, s76, 64
	s_mov_b32 m0, s16
	v_add_u32_e32 v164, s93, v231
	v_med3_i32 v164, v164, 0, s40
	v_lshl_or_b32 v164, v164, 7, v222
	global_load_lds_dwordx4 v164, s[24:25]
	s_add_i32 m0, s16, 0x400
	v_add_u32_e32 v165, s93, v232
	v_med3_i32 v165, v165, 0, s40
	v_lshl_or_b32 v165, v165, 7, v222
	global_load_lds_dwordx4 v165, s[24:25]
	s_waitcnt vmcnt(8)
	v_add_u32_e32 v154, s12, v225
	v_add_u32_e32 v155, s12, v226
	v_add_u32_e32 v156, s12, v227
	v_add_u32_e32 v157, s12, v228
	ds_read_b64_tr_b16 v[202:203], v154
	ds_read_b64_tr_b16 v[204:205], v155
	ds_read_b64_tr_b16 v[206:207], v156
	ds_read_b64_tr_b16 v[208:209], v157
	v_mfma_f32_16x16x16_bf16 v[96:99], v[88:89], v[0:1], 0
	v_mfma_f32_16x16x16_bf16 v[100:103], v[90:91], v[0:1], 0
	v_mfma_f32_16x16x16_bf16 v[104:107], v[92:93], v[0:1], 0
	v_mfma_f32_16x16x16_bf16 v[108:111], v[94:95], v[0:1], 0
	v_pk_add_f32 v[4:5], v[4:5], v[184:185] op_sel_hi:[1,0] neg_lo:[0,1] neg_hi:[0,1]
	v_pk_add_f32 v[6:7], v[6:7], v[184:185] op_sel_hi:[1,0] neg_lo:[0,1] neg_hi:[0,1]
	v_exp_f32_e32 v4, v4
	v_exp_f32_e32 v5, v5
	v_exp_f32_e32 v6, v6
	v_exp_f32_e32 v7, v7
	s_nop 0
	v_pk_add_f32 v[74:75], v[4:5], v[6:7]
	v_cvt_pk_bf16_f32 v4, v4, v5
	v_cvt_pk_bf16_f32 v5, v6, v7
	v_pk_add_f32 v[36:37], v[36:37], v[186:187] op_sel_hi:[1,0] neg_lo:[0,1] neg_hi:[0,1]
	v_pk_add_f32 v[38:39], v[38:39], v[186:187] op_sel_hi:[1,0] neg_lo:[0,1] neg_hi:[0,1]
	v_exp_f32_e32 v36, v36
	v_exp_f32_e32 v37, v37
	v_exp_f32_e32 v38, v38
	v_exp_f32_e32 v39, v39
	s_nop 0
	v_pk_add_f32 v[76:77], v[36:37], v[38:39]
	v_cvt_pk_bf16_f32 v36, v36, v37
	v_cvt_pk_bf16_f32 v37, v38, v39
	s_waitcnt lgkmcnt(0)
	s_add_i32 s93, s76, 0x80
	s_mov_b32 m0, s12
	v_add_u32_e32 v164, s93, v231
	v_med3_i32 v164, v164, 0, s40
	v_lshl_or_b32 v164, v164, 7, v222
	global_load_lds_dwordx4 v164, s[24:25]
	s_add_i32 m0, s12, 0x400
	v_add_u32_e32 v165, s93, v232
	v_med3_i32 v165, v165, 0, s40
	v_lshl_or_b32 v165, v165, 7, v222
	global_load_lds_dwordx4 v165, s[24:25]
	s_waitcnt vmcnt(8)
	v_add_u32_e32 v154, s13, v225
	v_add_u32_e32 v155, s13, v226
	v_add_u32_e32 v156, s13, v227
	v_add_u32_e32 v157, s13, v228
	ds_read_b64_tr_b16 v[88:89], v154
	ds_read_b64_tr_b16 v[90:91], v155
	ds_read_b64_tr_b16 v[92:93], v156
	ds_read_b64_tr_b16 v[94:95], v157
	v_mfma_f32_16x16x16_bf16 v[96:99], v[202:203], v[4:5], v[96:99]
	v_mfma_f32_16x16x16_bf16 v[112:115], v[202:203], v[36:37], 0
	v_mfma_f32_16x16x16_bf16 v[100:103], v[204:205], v[4:5], v[100:103]
	v_mfma_f32_16x16x16_bf16 v[116:119], v[204:205], v[36:37], 0
	v_mfma_f32_16x16x16_bf16 v[104:107], v[206:207], v[4:5], v[104:107]
	v_mfma_f32_16x16x16_bf16 v[120:123], v[206:207], v[36:37], 0
	v_mfma_f32_16x16x16_bf16 v[108:111], v[208:209], v[4:5], v[108:111]
	v_mfma_f32_16x16x16_bf16 v[124:127], v[208:209], v[36:37], 0
	v_pk_add_f32 v[8:9], v[8:9], v[184:185] op_sel_hi:[1,0] neg_lo:[0,1] neg_hi:[0,1]
	v_pk_add_f32 v[10:11], v[10:11], v[184:185] op_sel_hi:[1,0] neg_lo:[0,1] neg_hi:[0,1]
	v_exp_f32_e32 v8, v8
	v_exp_f32_e32 v9, v9
	v_exp_f32_e32 v10, v10
	v_exp_f32_e32 v11, v11
	s_nop 0
	v_pk_add_f32 v[72:73], v[72:73], v[8:9]
	v_pk_add_f32 v[74:75], v[74:75], v[10:11]
	v_cvt_pk_bf16_f32 v8, v8, v9
	v_cvt_pk_bf16_f32 v9, v10, v11
	v_pk_add_f32 v[40:41], v[40:41], v[186:187] op_sel_hi:[1,0] neg_lo:[0,1] neg_hi:[0,1]
	v_pk_add_f32 v[42:43], v[42:43], v[186:187] op_sel_hi:[1,0] neg_lo:[0,1] neg_hi:[0,1]
	v_exp_f32_e32 v40, v40
	v_exp_f32_e32 v41, v41
	v_exp_f32_e32 v42, v42
	v_exp_f32_e32 v43, v43
	s_nop 0
	v_pk_add_f32 v[78:79], v[40:41], v[42:43]
	v_cvt_pk_bf16_f32 v40, v40, v41
	v_cvt_pk_bf16_f32 v41, v42, v43
	s_waitcnt lgkmcnt(0)
	s_add_i32 s93, s76, 0xc0
	s_mov_b32 m0, s13
	v_add_u32_e32 v164, s93, v231
	v_med3_i32 v164, v164, 0, s40
	v_lshl_or_b32 v164, v164, 7, v222
	global_load_lds_dwordx4 v164, s[24:25]
	s_add_i32 m0, s13, 0x400
	v_add_u32_e32 v165, s93, v232
	v_med3_i32 v165, v165, 0, s40
	v_lshl_or_b32 v165, v165, 7, v222
	global_load_lds_dwordx4 v165, s[24:25]
	s_waitcnt vmcnt(8)
	v_add_u32_e32 v154, s14, v225
	v_add_u32_e32 v155, s14, v226
	v_add_u32_e32 v156, s14, v227
	v_add_u32_e32 v157, s14, v228
	ds_read_b64_tr_b16 v[202:203], v154
	ds_read_b64_tr_b16 v[204:205], v155
	ds_read_b64_tr_b16 v[206:207], v156
	ds_read_b64_tr_b16 v[208:209], v157
	v_mfma_f32_16x16x16_bf16 v[96:99], v[88:89], v[8:9], v[96:99]
	v_mfma_f32_16x16x16_bf16 v[112:115], v[88:89], v[40:41], v[112:115]
	v_mfma_f32_16x16x16_bf16 v[100:103], v[90:91], v[8:9], v[100:103]
	v_mfma_f32_16x16x16_bf16 v[116:119], v[90:91], v[40:41], v[116:119]
	v_mfma_f32_16x16x16_bf16 v[104:107], v[92:93], v[8:9], v[104:107]
	v_mfma_f32_16x16x16_bf16 v[120:123], v[92:93], v[40:41], v[120:123]
	v_mfma_f32_16x16x16_bf16 v[108:111], v[94:95], v[8:9], v[108:111]
	v_mfma_f32_16x16x16_bf16 v[124:127], v[94:95], v[40:41], v[124:127]
	v_pk_add_f32 v[12:13], v[12:13], v[184:185] op_sel_hi:[1,0] neg_lo:[0,1] neg_hi:[0,1]
	v_pk_add_f32 v[14:15], v[14:15], v[184:185] op_sel_hi:[1,0] neg_lo:[0,1] neg_hi:[0,1]
	v_exp_f32_e32 v12, v12
	v_exp_f32_e32 v13, v13
	v_exp_f32_e32 v14, v14
	v_exp_f32_e32 v15, v15
	s_nop 0
	v_pk_add_f32 v[72:73], v[72:73], v[12:13]
	v_pk_add_f32 v[74:75], v[74:75], v[14:15]
	v_cvt_pk_bf16_f32 v12, v12, v13
	v_cvt_pk_bf16_f32 v13, v14, v15
	v_pk_add_f32 v[44:45], v[44:45], v[186:187] op_sel_hi:[1,0] neg_lo:[0,1] neg_hi:[0,1]
	v_pk_add_f32 v[46:47], v[46:47], v[186:187] op_sel_hi:[1,0] neg_lo:[0,1] neg_hi:[0,1]
	v_exp_f32_e32 v44, v44
	v_exp_f32_e32 v45, v45
	v_exp_f32_e32 v46, v46
	v_exp_f32_e32 v47, v47
	s_nop 0
	v_pk_add_f32 v[76:77], v[76:77], v[44:45]
	v_pk_add_f32 v[78:79], v[78:79], v[46:47]
	v_cvt_pk_bf16_f32 v44, v44, v45
	v_cvt_pk_bf16_f32 v45, v46, v47
	s_waitcnt lgkmcnt(0)
	s_add_i32 s93, s76, 0x100
	s_mov_b32 m0, s14
	v_add_u32_e32 v164, s93, v231
	v_med3_i32 v164, v164, 0, s40
	v_lshl_or_b32 v164, v164, 7, v222
	global_load_lds_dwordx4 v164, s[24:25]
	s_add_i32 m0, s14, 0x400
	v_add_u32_e32 v165, s93, v232
	v_med3_i32 v165, v165, 0, s40
	v_lshl_or_b32 v165, v165, 7, v222
	global_load_lds_dwordx4 v165, s[24:25]
	s_waitcnt vmcnt(8)
	v_add_u32_e32 v154, s15, v225
	v_add_u32_e32 v155, s15, v226
	v_add_u32_e32 v156, s15, v227
	v_add_u32_e32 v157, s15, v228
	ds_read_b64_tr_b16 v[88:89], v154
	ds_read_b64_tr_b16 v[90:91], v155
	ds_read_b64_tr_b16 v[92:93], v156
	ds_read_b64_tr_b16 v[94:95], v157
	v_mfma_f32_16x16x16_bf16 v[96:99], v[202:203], v[12:13], v[96:99]
	v_mfma_f32_16x16x16_bf16 v[112:115], v[202:203], v[44:45], v[112:115]
	v_mfma_f32_16x16x16_bf16 v[100:103], v[204:205], v[12:13], v[100:103]
	v_mfma_f32_16x16x16_bf16 v[116:119], v[204:205], v[44:45], v[116:119]
	v_mfma_f32_16x16x16_bf16 v[104:107], v[206:207], v[12:13], v[104:107]
	v_mfma_f32_16x16x16_bf16 v[120:123], v[206:207], v[44:45], v[120:123]
	v_mfma_f32_16x16x16_bf16 v[108:111], v[208:209], v[12:13], v[108:111]
	v_mfma_f32_16x16x16_bf16 v[124:127], v[208:209], v[44:45], v[124:127]
	v_pk_add_f32 v[16:17], v[16:17], v[184:185] op_sel_hi:[1,0] neg_lo:[0,1] neg_hi:[0,1]
	v_pk_add_f32 v[18:19], v[18:19], v[184:185] op_sel_hi:[1,0] neg_lo:[0,1] neg_hi:[0,1]
	v_exp_f32_e32 v16, v16
	v_exp_f32_e32 v17, v17
	v_exp_f32_e32 v18, v18
	v_exp_f32_e32 v19, v19
	s_nop 0
	v_pk_add_f32 v[72:73], v[72:73], v[16:17]
	v_pk_add_f32 v[74:75], v[74:75], v[18:19]
	v_cvt_pk_bf16_f32 v16, v16, v17
	v_cvt_pk_bf16_f32 v17, v18, v19
	v_pk_add_f32 v[48:49], v[48:49], v[186:187] op_sel_hi:[1,0] neg_lo:[0,1] neg_hi:[0,1]
	v_pk_add_f32 v[50:51], v[50:51], v[186:187] op_sel_hi:[1,0] neg_lo:[0,1] neg_hi:[0,1]
	v_exp_f32_e32 v48, v48
	v_exp_f32_e32 v49, v49
	v_exp_f32_e32 v50, v50
	v_exp_f32_e32 v51, v51
	s_nop 0
	v_pk_add_f32 v[76:77], v[76:77], v[48:49]
	v_pk_add_f32 v[78:79], v[78:79], v[50:51]
	v_cvt_pk_bf16_f32 v48, v48, v49
	v_cvt_pk_bf16_f32 v49, v50, v51
	s_waitcnt lgkmcnt(0)
	s_add_i32 s93, s76, 0x140
	s_mov_b32 m0, s15
	v_add_u32_e32 v164, s93, v231
	v_med3_i32 v164, v164, 0, s40
	v_lshl_or_b32 v164, v164, 7, v222
	global_load_lds_dwordx4 v164, s[24:25]
	s_add_i32 m0, s15, 0x400
	v_add_u32_e32 v165, s93, v232
	v_med3_i32 v165, v165, 0, s40
	v_lshl_or_b32 v165, v165, 7, v222
	global_load_lds_dwordx4 v165, s[24:25]
	s_waitcnt vmcnt(8)
	v_add_u32_e32 v154, s16, v225
	v_add_u32_e32 v155, s16, v226
	v_add_u32_e32 v156, s16, v227
	v_add_u32_e32 v157, s16, v228
	ds_read_b64_tr_b16 v[202:203], v154
	ds_read_b64_tr_b16 v[204:205], v155
	ds_read_b64_tr_b16 v[206:207], v156
	ds_read_b64_tr_b16 v[208:209], v157
	v_mfma_f32_16x16x16_bf16 v[96:99], v[88:89], v[16:17], v[96:99]
	v_mfma_f32_16x16x16_bf16 v[112:115], v[88:89], v[48:49], v[112:115]
	v_mfma_f32_16x16x16_bf16 v[100:103], v[90:91], v[16:17], v[100:103]
	v_mfma_f32_16x16x16_bf16 v[116:119], v[90:91], v[48:49], v[116:119]
	v_mfma_f32_16x16x16_bf16 v[104:107], v[92:93], v[16:17], v[104:107]
	v_mfma_f32_16x16x16_bf16 v[120:123], v[92:93], v[48:49], v[120:123]
	v_mfma_f32_16x16x16_bf16 v[108:111], v[94:95], v[16:17], v[108:111]
	v_mfma_f32_16x16x16_bf16 v[124:127], v[94:95], v[48:49], v[124:127]
	v_pk_add_f32 v[20:21], v[20:21], v[184:185] op_sel_hi:[1,0] neg_lo:[0,1] neg_hi:[0,1]
	v_pk_add_f32 v[22:23], v[22:23], v[184:185] op_sel_hi:[1,0] neg_lo:[0,1] neg_hi:[0,1]
	v_exp_f32_e32 v20, v20
	v_exp_f32_e32 v21, v21
	v_exp_f32_e32 v22, v22
	v_exp_f32_e32 v23, v23
	s_nop 0
	v_pk_add_f32 v[72:73], v[72:73], v[20:21]
	v_pk_add_f32 v[74:75], v[74:75], v[22:23]
	v_cvt_pk_bf16_f32 v20, v20, v21
	v_cvt_pk_bf16_f32 v21, v22, v23
	v_pk_add_f32 v[52:53], v[52:53], v[186:187] op_sel_hi:[1,0] neg_lo:[0,1] neg_hi:[0,1]
	v_pk_add_f32 v[54:55], v[54:55], v[186:187] op_sel_hi:[1,0] neg_lo:[0,1] neg_hi:[0,1]
	v_exp_f32_e32 v52, v52
	v_exp_f32_e32 v53, v53
	v_exp_f32_e32 v54, v54
	v_exp_f32_e32 v55, v55
	s_nop 0
	v_pk_add_f32 v[76:77], v[76:77], v[52:53]
	v_pk_add_f32 v[78:79], v[78:79], v[54:55]
	v_cvt_pk_bf16_f32 v52, v52, v53
	v_cvt_pk_bf16_f32 v53, v54, v55
	s_waitcnt lgkmcnt(0)
	s_add_i32 s93, s79, 0
	s_mov_b32 m0, s16
	v_add_u32_e32 v164, s93, v162
	v_lshl_or_b32 v164, v164, 7, v220
	global_load_lds_dwordx4 v164, s[18:19]
	s_add_i32 m0, s16, 0x400
	v_add_u32_e32 v165, s93, v163
	v_lshl_or_b32 v165, v165, 7, v221
	global_load_lds_dwordx4 v165, s[18:19]
	s_waitcnt vmcnt(8)
	v_add_u32_e32 v154, s12, v225
	v_add_u32_e32 v155, s12, v226
	v_add_u32_e32 v156, s12, v227
	v_add_u32_e32 v157, s12, v228
	ds_read_b64_tr_b16 v[88:89], v154
	ds_read_b64_tr_b16 v[90:91], v155
	ds_read_b64_tr_b16 v[92:93], v156
	ds_read_b64_tr_b16 v[94:95], v157
	v_mfma_f32_16x16x16_bf16 v[96:99], v[202:203], v[20:21], v[96:99]
	v_mfma_f32_16x16x16_bf16 v[112:115], v[202:203], v[52:53], v[112:115]
	v_mfma_f32_16x16x16_bf16 v[100:103], v[204:205], v[20:21], v[100:103]
	v_mfma_f32_16x16x16_bf16 v[116:119], v[204:205], v[52:53], v[116:119]
	v_mfma_f32_16x16x16_bf16 v[104:107], v[206:207], v[20:21], v[104:107]
	v_mfma_f32_16x16x16_bf16 v[120:123], v[206:207], v[52:53], v[120:123]
	v_mfma_f32_16x16x16_bf16 v[108:111], v[208:209], v[20:21], v[108:111]
	v_mfma_f32_16x16x16_bf16 v[124:127], v[208:209], v[52:53], v[124:127]
	v_pk_add_f32 v[24:25], v[24:25], v[184:185] op_sel_hi:[1,0] neg_lo:[0,1] neg_hi:[0,1]
	v_pk_add_f32 v[26:27], v[26:27], v[184:185] op_sel_hi:[1,0] neg_lo:[0,1] neg_hi:[0,1]
	v_exp_f32_e32 v24, v24
	v_exp_f32_e32 v25, v25
	v_exp_f32_e32 v26, v26
	v_exp_f32_e32 v27, v27
	s_nop 0
	v_pk_add_f32 v[72:73], v[72:73], v[24:25]
	v_pk_add_f32 v[74:75], v[74:75], v[26:27]
	v_cvt_pk_bf16_f32 v24, v24, v25
	v_cvt_pk_bf16_f32 v25, v26, v27
	v_pk_add_f32 v[56:57], v[56:57], v[186:187] op_sel_hi:[1,0] neg_lo:[0,1] neg_hi:[0,1]
	v_pk_add_f32 v[58:59], v[58:59], v[186:187] op_sel_hi:[1,0] neg_lo:[0,1] neg_hi:[0,1]
	v_exp_f32_e32 v56, v56
	v_exp_f32_e32 v57, v57
	v_exp_f32_e32 v58, v58
	v_exp_f32_e32 v59, v59
	s_nop 0
	v_pk_add_f32 v[76:77], v[76:77], v[56:57]
	v_pk_add_f32 v[78:79], v[78:79], v[58:59]
	v_cvt_pk_bf16_f32 v56, v56, v57
	v_cvt_pk_bf16_f32 v57, v58, v59
	s_waitcnt lgkmcnt(0)
	s_add_i32 s93, s79, 0xfffffc00
	s_mov_b32 m0, s12
	v_add_u32_e32 v164, s93, v162
	v_med3_i32 v164, v164, 0, s40
	v_lshl_or_b32 v164, v164, 7, v220
	global_load_lds_dwordx4 v164, s[20:21]
	s_add_i32 m0, s12, 0x400
	v_add_u32_e32 v165, s93, v163
	v_med3_i32 v165, v165, 0, s40
	v_lshl_or_b32 v165, v165, 7, v221
	global_load_lds_dwordx4 v165, s[20:21]
	s_waitcnt vmcnt(8)
	v_add_u32_e32 v154, s13, v225
	v_add_u32_e32 v155, s13, v226
	v_add_u32_e32 v156, s13, v227
	v_add_u32_e32 v157, s13, v228
	ds_read_b64_tr_b16 v[202:203], v154
	ds_read_b64_tr_b16 v[204:205], v155
	ds_read_b64_tr_b16 v[206:207], v156
	ds_read_b64_tr_b16 v[208:209], v157
	v_mfma_f32_16x16x16_bf16 v[96:99], v[88:89], v[24:25], v[96:99]
	v_mfma_f32_16x16x16_bf16 v[112:115], v[88:89], v[56:57], v[112:115]
	v_mfma_f32_16x16x16_bf16 v[100:103], v[90:91], v[24:25], v[100:103]
	v_mfma_f32_16x16x16_bf16 v[116:119], v[90:91], v[56:57], v[116:119]
	v_mfma_f32_16x16x16_bf16 v[104:107], v[92:93], v[24:25], v[104:107]
	v_mfma_f32_16x16x16_bf16 v[120:123], v[92:93], v[56:57], v[120:123]
	v_mfma_f32_16x16x16_bf16 v[108:111], v[94:95], v[24:25], v[108:111]
	v_mfma_f32_16x16x16_bf16 v[124:127], v[94:95], v[56:57], v[124:127]
	v_pk_add_f32 v[28:29], v[28:29], v[184:185] op_sel_hi:[1,0] neg_lo:[0,1] neg_hi:[0,1]
	v_pk_add_f32 v[30:31], v[30:31], v[184:185] op_sel_hi:[1,0] neg_lo:[0,1] neg_hi:[0,1]
	v_exp_f32_e32 v28, v28
	v_exp_f32_e32 v29, v29
	v_exp_f32_e32 v30, v30
	v_exp_f32_e32 v31, v31
	s_nop 0
	v_pk_add_f32 v[72:73], v[72:73], v[28:29]
	v_pk_add_f32 v[74:75], v[74:75], v[30:31]
	v_cvt_pk_bf16_f32 v28, v28, v29
	v_cvt_pk_bf16_f32 v29, v30, v31
	v_pk_add_f32 v[60:61], v[60:61], v[186:187] op_sel_hi:[1,0] neg_lo:[0,1] neg_hi:[0,1]
	v_pk_add_f32 v[62:63], v[62:63], v[186:187] op_sel_hi:[1,0] neg_lo:[0,1] neg_hi:[0,1]
	v_exp_f32_e32 v60, v60
	v_exp_f32_e32 v61, v61
	v_exp_f32_e32 v62, v62
	v_exp_f32_e32 v63, v63
	s_nop 0
	v_pk_add_f32 v[76:77], v[76:77], v[60:61]
	v_pk_add_f32 v[78:79], v[78:79], v[62:63]
	v_cvt_pk_bf16_f32 v60, v60, v61
	v_cvt_pk_bf16_f32 v61, v62, v63
	s_waitcnt lgkmcnt(0)
	s_add_i32 s93, s79, 0xfffffd00
	s_mov_b32 m0, s13
	v_add_u32_e32 v164, s93, v162
	v_med3_i32 v164, v164, 0, s40
	v_lshl_or_b32 v164, v164, 7, v220
	global_load_lds_dwordx4 v164, s[20:21]
	s_add_i32 m0, s13, 0x400
	v_add_u32_e32 v165, s93, v163
	v_med3_i32 v165, v165, 0, s40
	v_lshl_or_b32 v165, v165, 7, v221
	global_load_lds_dwordx4 v165, s[20:21]
	s_waitcnt vmcnt(8)
	v_add_u32_e32 v154, s14, v225
	v_add_u32_e32 v155, s14, v226
	v_add_u32_e32 v156, s14, v227
	v_add_u32_e32 v157, s14, v228
	ds_read_b64_tr_b16 v[88:89], v154
	ds_read_b64_tr_b16 v[90:91], v155
	ds_read_b64_tr_b16 v[92:93], v156
	ds_read_b64_tr_b16 v[94:95], v157
	v_mfma_f32_16x16x16_bf16 v[96:99], v[202:203], v[28:29], v[96:99]
	v_mfma_f32_16x16x16_bf16 v[112:115], v[202:203], v[60:61], v[112:115]
	v_mfma_f32_16x16x16_bf16 v[100:103], v[204:205], v[28:29], v[100:103]
	v_mfma_f32_16x16x16_bf16 v[116:119], v[204:205], v[60:61], v[116:119]
	v_mfma_f32_16x16x16_bf16 v[104:107], v[206:207], v[28:29], v[104:107]
	v_mfma_f32_16x16x16_bf16 v[120:123], v[206:207], v[60:61], v[120:123]
	v_mfma_f32_16x16x16_bf16 v[108:111], v[208:209], v[28:29], v[108:111]
	v_mfma_f32_16x16x16_bf16 v[124:127], v[208:209], v[60:61], v[124:127]
	v_pk_add_f32 v[32:33], v[32:33], v[184:185] op_sel_hi:[1,0] neg_lo:[0,1] neg_hi:[0,1]
	v_pk_add_f32 v[34:35], v[34:35], v[184:185] op_sel_hi:[1,0] neg_lo:[0,1] neg_hi:[0,1]
	v_exp_f32_e32 v32, v32
	v_exp_f32_e32 v33, v33
	v_exp_f32_e32 v34, v34
	v_exp_f32_e32 v35, v35
	s_nop 0
	v_pk_add_f32 v[72:73], v[72:73], v[32:33]
	v_pk_add_f32 v[74:75], v[74:75], v[34:35]
	v_cvt_pk_bf16_f32 v32, v32, v33
	v_cvt_pk_bf16_f32 v33, v34, v35
	v_pk_add_f32 v[64:65], v[64:65], v[186:187] op_sel_hi:[1,0] neg_lo:[0,1] neg_hi:[0,1]
	v_pk_add_f32 v[66:67], v[66:67], v[186:187] op_sel_hi:[1,0] neg_lo:[0,1] neg_hi:[0,1]
	v_exp_f32_e32 v64, v64
	v_exp_f32_e32 v65, v65
	v_exp_f32_e32 v66, v66
	v_exp_f32_e32 v67, v67
	s_nop 0
	v_pk_add_f32 v[76:77], v[76:77], v[64:65]
	v_pk_add_f32 v[78:79], v[78:79], v[66:67]
	v_cvt_pk_bf16_f32 v64, v64, v65
	v_cvt_pk_bf16_f32 v65, v66, v67
	s_waitcnt lgkmcnt(0)
	s_add_i32 s93, s79, 0xfffffe00
	s_mov_b32 m0, s14
	v_add_u32_e32 v164, s93, v162
	v_med3_i32 v164, v164, 0, s40
	v_lshl_or_b32 v164, v164, 7, v220
	global_load_lds_dwordx4 v164, s[20:21]
	s_add_i32 m0, s14, 0x400
	v_add_u32_e32 v165, s93, v163
	v_med3_i32 v165, v165, 0, s40
	v_lshl_or_b32 v165, v165, 7, v221
	global_load_lds_dwordx4 v165, s[20:21]
	s_waitcnt vmcnt(8)
	v_add_u32_e32 v154, s15, v225
	v_add_u32_e32 v155, s15, v226
	v_add_u32_e32 v156, s15, v227
	v_add_u32_e32 v157, s15, v228
	ds_read_b64_tr_b16 v[202:203], v154
	ds_read_b64_tr_b16 v[204:205], v155
	ds_read_b64_tr_b16 v[206:207], v156
	ds_read_b64_tr_b16 v[208:209], v157
	v_mfma_f32_16x16x16_bf16 v[96:99], v[88:89], v[32:33], v[96:99]
	v_mfma_f32_16x16x16_bf16 v[112:115], v[88:89], v[64:65], v[112:115]
	v_mfma_f32_16x16x16_bf16 v[100:103], v[90:91], v[32:33], v[100:103]
	v_mfma_f32_16x16x16_bf16 v[116:119], v[90:91], v[64:65], v[116:119]
	v_mfma_f32_16x16x16_bf16 v[104:107], v[92:93], v[32:33], v[104:107]
	v_mfma_f32_16x16x16_bf16 v[120:123], v[92:93], v[64:65], v[120:123]
	v_mfma_f32_16x16x16_bf16 v[108:111], v[94:95], v[32:33], v[108:111]
	v_mfma_f32_16x16x16_bf16 v[124:127], v[94:95], v[64:65], v[124:127]
	v_pk_add_f32 v[68:69], v[68:69], v[186:187] op_sel_hi:[1,0] neg_lo:[0,1] neg_hi:[0,1]
	v_pk_add_f32 v[70:71], v[70:71], v[186:187] op_sel_hi:[1,0] neg_lo:[0,1] neg_hi:[0,1]
	v_exp_f32_e32 v68, v68
	v_exp_f32_e32 v69, v69
	v_exp_f32_e32 v70, v70
	v_exp_f32_e32 v71, v71
	s_nop 0
	v_pk_add_f32 v[76:77], v[76:77], v[68:69]
	v_pk_add_f32 v[78:79], v[78:79], v[70:71]
	v_cvt_pk_bf16_f32 v68, v68, v69
	v_cvt_pk_bf16_f32 v69, v70, v71
	s_nop 0
	v_pk_add_f32 v[72:73], v[72:73], v[74:75]
	s_nop 0
	v_add_f32_e32 v185, v72, v73
	v_mov_b32_e32 v146, v185
	s_nop 1
	v_permlane16_swap_b32_e32 v185, v146
	v_add_f32_e32 v185, v185, v146
	v_mov_b32_e32 v146, v185
	s_nop 1
	v_permlane32_swap_b32_e32 v185, v146
	v_add_f32_e32 v185, v185, v146
	s_waitcnt lgkmcnt(0)
	s_add_i32 s93, s79, 0xffffff00
	s_mov_b32 m0, s15
	v_add_u32_e32 v164, s93, v162
	v_med3_i32 v164, v164, 0, s40
	v_lshl_or_b32 v164, v164, 7, v220
	global_load_lds_dwordx4 v164, s[20:21]
	s_add_i32 m0, s15, 0x400
	v_add_u32_e32 v165, s93, v163
	v_med3_i32 v165, v165, 0, s40
	v_lshl_or_b32 v165, v165, 7, v221
	global_load_lds_dwordx4 v165, s[20:21]
	v_mfma_f32_16x16x16_bf16 v[112:115], v[202:203], v[68:69], v[112:115]
	v_mfma_f32_16x16x16_bf16 v[116:119], v[204:205], v[68:69], v[116:119]
	v_mfma_f32_16x16x16_bf16 v[120:123], v[206:207], v[68:69], v[120:123]
	v_mfma_f32_16x16x16_bf16 v[124:127], v[208:209], v[68:69], v[124:127]
	s_nop 0
	v_pk_add_f32 v[76:77], v[76:77], v[78:79]
	s_nop 0
	v_add_f32_e32 v187, v76, v77
	v_mov_b32_e32 v146, v187
	s_nop 1
	v_permlane16_swap_b32_e32 v187, v146
	v_add_f32_e32 v187, v187, v146
	v_mov_b32_e32 v146, v187
	s_nop 1
	v_permlane32_swap_b32_e32 v187, v146
	v_add_f32_e32 v187, v187, v146
	s_waitcnt lgkmcnt(0)
	v_max_f32_e32 v146, v144, v184
	v_sub_f32_e32 v148, v144, v146
	v_sub_f32_e32 v150, v184, v146
	v_exp_f32_e32 v148, v148
	v_exp_f32_e32 v150, v150
	v_mov_b32_e32 v184, v146
	v_mul_f32_e32 v185, v185, v150
	v_fmac_f32_e32 v185, v145, v148
	v_pk_mul_f32 v[96:97], v[150:151], v[96:97] op_sel_hi:[0,1]
	v_pk_mul_f32 v[98:99], v[150:151], v[98:99] op_sel_hi:[0,1]
	v_pk_mul_f32 v[100:101], v[150:151], v[100:101] op_sel_hi:[0,1]
	v_pk_mul_f32 v[102:103], v[150:151], v[102:103] op_sel_hi:[0,1]
	v_pk_mul_f32 v[104:105], v[150:151], v[104:105] op_sel_hi:[0,1]
	v_pk_mul_f32 v[106:107], v[150:151], v[106:107] op_sel_hi:[0,1]
	v_pk_mul_f32 v[108:109], v[150:151], v[108:109] op_sel_hi:[0,1]
	v_pk_mul_f32 v[110:111], v[150:151], v[110:111] op_sel_hi:[0,1]
	v_pk_fma_f32 v[96:97], v[148:149], v[128:129], v[96:97] op_sel_hi:[0,1,1]
	v_pk_fma_f32 v[98:99], v[148:149], v[130:131], v[98:99] op_sel_hi:[0,1,1]
	v_pk_fma_f32 v[100:101], v[148:149], v[132:133], v[100:101] op_sel_hi:[0,1,1]
	v_pk_fma_f32 v[102:103], v[148:149], v[134:135], v[102:103] op_sel_hi:[0,1,1]
	v_pk_fma_f32 v[104:105], v[148:149], v[136:137], v[104:105] op_sel_hi:[0,1,1]
	v_pk_fma_f32 v[106:107], v[148:149], v[138:139], v[106:107] op_sel_hi:[0,1,1]
	v_pk_fma_f32 v[108:109], v[148:149], v[140:141], v[108:109] op_sel_hi:[0,1,1]
	v_pk_fma_f32 v[110:111], v[148:149], v[142:143], v[110:111] op_sel_hi:[0,1,1]
	s_and_saveexec_b64 s[80:81], s[74:75]
	ds_write_b64 v194, v[184:185]
	s_mov_b64 exec, s[80:81]
	ds_write_b128 v190, v[96:99]
	ds_write_b128 v191, v[100:103]
	ds_write_b128 v192, v[104:107]
	ds_write_b128 v193, v[108:111]
	s_waitcnt lgkmcnt(0)
	v_max_f32_e32 v146, v182, v186
	v_sub_f32_e32 v148, v182, v146
	v_sub_f32_e32 v150, v186, v146
	v_exp_f32_e32 v148, v148
	v_exp_f32_e32 v150, v150
	v_mov_b32_e32 v186, v146
	v_mul_f32_e32 v187, v187, v150
	v_fmac_f32_e32 v187, v183, v148
	v_pk_mul_f32 v[112:113], v[150:151], v[112:113] op_sel_hi:[0,1]
	v_pk_mul_f32 v[114:115], v[150:151], v[114:115] op_sel_hi:[0,1]
	v_pk_mul_f32 v[116:117], v[150:151], v[116:117] op_sel_hi:[0,1]
	v_pk_mul_f32 v[118:119], v[150:151], v[118:119] op_sel_hi:[0,1]
	v_pk_mul_f32 v[120:121], v[150:151], v[120:121] op_sel_hi:[0,1]
	v_pk_mul_f32 v[122:123], v[150:151], v[122:123] op_sel_hi:[0,1]
	v_pk_mul_f32 v[124:125], v[150:151], v[124:125] op_sel_hi:[0,1]
	v_pk_mul_f32 v[126:127], v[150:151], v[126:127] op_sel_hi:[0,1]
	v_pk_fma_f32 v[112:113], v[148:149], v[166:167], v[112:113] op_sel_hi:[0,1,1]
	v_pk_fma_f32 v[114:115], v[148:149], v[168:169], v[114:115] op_sel_hi:[0,1,1]
	v_pk_fma_f32 v[116:117], v[148:149], v[170:171], v[116:117] op_sel_hi:[0,1,1]
	v_pk_fma_f32 v[118:119], v[148:149], v[172:173], v[118:119] op_sel_hi:[0,1,1]
	v_pk_fma_f32 v[120:121], v[148:149], v[174:175], v[120:121] op_sel_hi:[0,1,1]
	v_pk_fma_f32 v[122:123], v[148:149], v[176:177], v[122:123] op_sel_hi:[0,1,1]
	v_pk_fma_f32 v[124:125], v[148:149], v[178:179], v[124:125] op_sel_hi:[0,1,1]
	v_pk_fma_f32 v[126:127], v[148:149], v[180:181], v[126:127] op_sel_hi:[0,1,1]
	s_and_saveexec_b64 s[80:81], s[74:75]
	ds_write_b64 v199, v[186:187]
	s_mov_b64 exec, s[80:81]
	ds_write_b128 v195, v[112:115]
	ds_write_b128 v196, v[116:119]
	ds_write_b128 v197, v[120:123]
	ds_write_b128 v198, v[124:127]
	s_waitcnt lgkmcnt(0)
	s_barrier
	s_add_i32 s76, s38, s84
	s_add_i32 s79, s39, s82
	v_lshlrev_b32_e32 v231, 4, v218
	v_add_u32_e32 v232, 8, v218
	v_lshlrev_b32_e32 v232, 4, v232
	v_lshlrev_b32_e32 v162, 0, v218
	v_add_u32_e32 v163, 8, v218
	v_lshlrev_b32_e32 v163, 0, v163
	s_add_i32 s8, s38, s85
	s_waitcnt vmcnt(8)
	v_add_u32_e32 v154, s16, v223
	v_add_u32_e32 v155, s16, v224
	ds_read_b128 v[72:75], v154
	ds_read_b128 v[76:79], v155
	s_waitcnt lgkmcnt(0)
	s_add_i32 s93, s76, 0
	s_mov_b32 m0, s16
	v_add_u32_e32 v164, s93, v231
	v_med3_i32 v164, v164, 0, s40
	v_lshl_or_b32 v164, v164, 7, v220
	global_load_lds_dwordx4 v164, s[20:21]
	s_add_i32 m0, s16, 0x400
	v_add_u32_e32 v165, s93, v232
	v_med3_i32 v165, v165, 0, s40
	v_lshl_or_b32 v165, v165, 7, v221
	global_load_lds_dwordx4 v165, s[20:21]
	s_waitcnt vmcnt(8)
	v_add_u32_e32 v154, s12, v223
	v_add_u32_e32 v155, s12, v224
	ds_read_b128 v[202:205], v154
	ds_read_b128 v[206:209], v155
	s_waitcnt lgkmcnt(0)
	s_add_i32 s93, s76, 0x100
	s_mov_b32 m0, s12
	v_add_u32_e32 v164, s93, v231
	v_med3_i32 v164, v164, 0, s40
	v_lshl_or_b32 v164, v164, 7, v220
	global_load_lds_dwordx4 v164, s[20:21]
	s_add_i32 m0, s12, 0x400
	v_add_u32_e32 v165, s93, v232
	v_med3_i32 v165, v165, 0, s40
	v_lshl_or_b32 v165, v165, 7, v221
	global_load_lds_dwordx4 v165, s[20:21]
	s_waitcnt vmcnt(8)
	v_add_u32_e32 v154, s13, v223
	v_add_u32_e32 v155, s13, v224
	ds_read_b128 v[88:91], v154
	ds_read_b128 v[92:95], v155
	v_mfma_f32_16x16x32_bf16 v[0:3], v[202:205], v[72:75], 0
	v_mfma_f32_16x16x32_bf16 v[0:3], v[206:209], v[76:79], v[0:3]
	s_waitcnt lgkmcnt(0)
	s_add_i32 s93, s76, 0x200
	s_mov_b32 m0, s13
	v_add_u32_e32 v164, s93, v231
	v_med3_i32 v164, v164, 0, s40
	v_lshl_or_b32 v164, v164, 7, v220
	global_load_lds_dwordx4 v164, s[20:21]
	s_add_i32 m0, s13, 0x400
	v_add_u32_e32 v165, s93, v232
	v_med3_i32 v165, v165, 0, s40
	v_lshl_or_b32 v165, v165, 7, v221
	global_load_lds_dwordx4 v165, s[20:21]
	s_waitcnt vmcnt(8)
	v_add_u32_e32 v154, s14, v223
	v_add_u32_e32 v155, s14, v224
	ds_read_b128 v[202:205], v154
	ds_read_b128 v[206:209], v155
	v_mfma_f32_16x16x32_bf16 v[4:7], v[88:91], v[72:75], 0
	v_mfma_f32_16x16x32_bf16 v[4:7], v[92:95], v[76:79], v[4:7]
	s_waitcnt lgkmcnt(0)
	s_add_i32 s93, s76, 0x300
	s_mov_b32 m0, s14
	v_add_u32_e32 v164, s93, v231
	v_med3_i32 v164, v164, 0, s40
	v_lshl_or_b32 v164, v164, 7, v220
	global_load_lds_dwordx4 v164, s[20:21]
	s_add_i32 m0, s14, 0x400
	v_add_u32_e32 v165, s93, v232
	v_med3_i32 v165, v165, 0, s40
	v_lshl_or_b32 v165, v165, 7, v221
	global_load_lds_dwordx4 v165, s[20:21]
	s_waitcnt vmcnt(8)
	v_add_u32_e32 v154, s15, v223
	v_add_u32_e32 v155, s15, v224
	ds_read_b128 v[88:91], v154
	ds_read_b128 v[92:95], v155
	v_mfma_f32_16x16x32_bf16 v[8:11], v[202:205], v[72:75], 0
	v_mfma_f32_16x16x32_bf16 v[8:11], v[206:209], v[76:79], v[8:11]
	s_waitcnt lgkmcnt(0)
	s_add_i32 s93, s76, 0x400
	s_mov_b32 m0, s15
	v_add_u32_e32 v164, s93, v231
	v_med3_i32 v164, v164, 0, s40
	v_lshl_or_b32 v164, v164, 7, v220
	global_load_lds_dwordx4 v164, s[20:21]
	s_add_i32 m0, s15, 0x400
	v_add_u32_e32 v165, s93, v232
	v_med3_i32 v165, v165, 0, s40
	v_lshl_or_b32 v165, v165, 7, v221
	global_load_lds_dwordx4 v165, s[20:21]
	s_waitcnt vmcnt(8)
	v_add_u32_e32 v154, s16, v223
	v_add_u32_e32 v155, s16, v224
	ds_read_b128 v[202:205], v154
	ds_read_b128 v[206:209], v155
	v_mfma_f32_16x16x32_bf16 v[12:15], v[88:91], v[72:75], 0
	v_mfma_f32_16x16x32_bf16 v[12:15], v[92:95], v[76:79], v[12:15]
	s_waitcnt lgkmcnt(0)
	s_add_i32 s93, s8, 0
	s_mov_b32 m0, s16
	v_add_u32_e32 v164, s93, v231
	v_lshl_or_b32 v164, v164, 7, v220
	global_load_lds_dwordx4 v164, s[18:19]
	s_add_i32 m0, s16, 0x400
	v_add_u32_e32 v165, s93, v232
	v_lshl_or_b32 v165, v165, 7, v221
	global_load_lds_dwordx4 v165, s[18:19]
	s_waitcnt vmcnt(8)
	v_add_u32_e32 v154, s12, v223
	v_add_u32_e32 v155, s12, v224
	ds_read_b128 v[88:91], v154
	ds_read_b128 v[92:95], v155
	v_mfma_f32_16x16x32_bf16 v[16:19], v[202:205], v[72:75], 0
	v_mfma_f32_16x16x32_bf16 v[16:19], v[206:209], v[76:79], v[16:19]
	s_waitcnt lgkmcnt(0)
	s_add_i32 s93, s8, 0xfffffc00
	s_mov_b32 m0, s12
	v_add_u32_e32 v164, s93, v231
	v_med3_i32 v164, v164, 0, s40
	v_lshl_or_b32 v164, v164, 7, v220
	global_load_lds_dwordx4 v164, s[20:21]
	s_add_i32 m0, s12, 0x400
	v_add_u32_e32 v165, s93, v232
	v_med3_i32 v165, v165, 0, s40
	v_lshl_or_b32 v165, v165, 7, v221
	global_load_lds_dwordx4 v165, s[20:21]
	s_waitcnt vmcnt(8)
	v_add_u32_e32 v154, s13, v223
	v_add_u32_e32 v155, s13, v224
	ds_read_b128 v[202:205], v154
	ds_read_b128 v[206:209], v155
	v_mfma_f32_16x16x32_bf16 v[20:23], v[88:91], v[72:75], 0
	v_mfma_f32_16x16x32_bf16 v[20:23], v[92:95], v[76:79], v[20:23]
	s_waitcnt lgkmcnt(0)
	s_add_i32 s93, s8, 0xfffffd00
	s_mov_b32 m0, s13
	v_add_u32_e32 v164, s93, v231
	v_med3_i32 v164, v164, 0, s40
	v_lshl_or_b32 v164, v164, 7, v220
	global_load_lds_dwordx4 v164, s[20:21]
	s_add_i32 m0, s13, 0x400
	v_add_u32_e32 v165, s93, v232
	v_med3_i32 v165, v165, 0, s40
	v_lshl_or_b32 v165, v165, 7, v221
	global_load_lds_dwordx4 v165, s[20:21]
	s_waitcnt vmcnt(8)
	v_add_u32_e32 v154, s14, v223
	v_add_u32_e32 v155, s14, v224
	ds_read_b128 v[88:91], v154
	ds_read_b128 v[92:95], v155
	v_mfma_f32_16x16x32_bf16 v[24:27], v[202:205], v[72:75], 0
	v_mfma_f32_16x16x32_bf16 v[24:27], v[206:209], v[76:79], v[24:27]
	s_waitcnt lgkmcnt(0)
	s_add_i32 s93, s8, 0xfffffe00
	s_mov_b32 m0, s14
	v_add_u32_e32 v164, s93, v231
	v_med3_i32 v164, v164, 0, s40
	v_lshl_or_b32 v164, v164, 7, v220
	global_load_lds_dwordx4 v164, s[20:21]
	s_add_i32 m0, s14, 0x400
	v_add_u32_e32 v165, s93, v232
	v_med3_i32 v165, v165, 0, s40
	v_lshl_or_b32 v165, v165, 7, v221
	global_load_lds_dwordx4 v165, s[20:21]
	s_waitcnt vmcnt(8)
	v_add_u32_e32 v154, s15, v223
	v_add_u32_e32 v155, s15, v224
	ds_read_b128 v[202:205], v154
	ds_read_b128 v[206:209], v155
	v_mfma_f32_16x16x32_bf16 v[28:31], v[88:91], v[72:75], 0
	v_mfma_f32_16x16x32_bf16 v[28:31], v[92:95], v[76:79], v[28:31]
	s_waitcnt lgkmcnt(0)
	s_add_i32 s93, s8, 0xffffff00
	s_mov_b32 m0, s15
	v_add_u32_e32 v164, s93, v231
	v_med3_i32 v164, v164, 0, s40
	v_lshl_or_b32 v164, v164, 7, v220
	global_load_lds_dwordx4 v164, s[20:21]
	s_add_i32 m0, s15, 0x400
	v_add_u32_e32 v165, s93, v232
	v_med3_i32 v165, v165, 0, s40
	v_lshl_or_b32 v165, v165, 7, v221
	global_load_lds_dwordx4 v165, s[20:21]
	s_waitcnt vmcnt(8)
	v_add_u32_e32 v154, s16, v223
	v_add_u32_e32 v155, s16, v224
	ds_read_b128 v[80:83], v154
	ds_read_b128 v[84:87], v155
	v_mfma_f32_16x16x32_bf16 v[32:35], v[202:205], v[72:75], 0
	v_mfma_f32_16x16x32_bf16 v[32:35], v[206:209], v[76:79], v[32:35]
	s_waitcnt lgkmcnt(0)
	s_add_i32 s93, s8, 0
	s_mov_b32 m0, s16
	v_add_u32_e32 v164, s93, v231
	v_med3_i32 v164, v164, 0, s40
	v_lshl_or_b32 v164, v164, 7, v220
	global_load_lds_dwordx4 v164, s[20:21]
	s_add_i32 m0, s16, 0x400
	v_add_u32_e32 v165, s93, v232
	v_med3_i32 v165, v165, 0, s40
	v_lshl_or_b32 v165, v165, 7, v221
	global_load_lds_dwordx4 v165, s[20:21]
	s_waitcnt vmcnt(8)
	v_add_u32_e32 v154, s12, v223
	v_add_u32_e32 v155, s12, v224
	ds_read_b128 v[202:205], v154
	ds_read_b128 v[206:209], v155
	v_mov_b32_e32 v188, s84
	v_lshl_add_u32 v188, v216, 4, v188
	v_lshrrev_b32_e32 v146, 4, v188
	v_xor_b32_e32 v146, v146, v188
	v_and_b32_e32 v146, 15, v146
	v_lshlrev_b32_e32 v147, 8, v188
	v_or_b32_e32 v148, 0, v217
	v_xor_b32_e32 v148, v148, v146
	v_lshl_add_u32 v190, v148, 4, v147
	v_or_b32_e32 v148, 4, v217
	v_xor_b32_e32 v148, v148, v146
	v_lshl_add_u32 v191, v148, 4, v147
	v_or_b32_e32 v148, 8, v217
	v_xor_b32_e32 v148, v148, v146
	v_lshl_add_u32 v192, v148, 4, v147
	v_or_b32_e32 v148, 12, v217
	v_xor_b32_e32 v148, v148, v146
	v_lshl_add_u32 v193, v148, 4, v147
	v_lshlrev_b32_e32 v194, 3, v188
	v_add_u32_e32 v194, 0x10000, v194
	ds_read_b64 v[144:145], v194
	ds_read_b128 v[128:131], v190
	ds_read_b128 v[132:135], v191
	ds_read_b128 v[136:139], v192
	ds_read_b128 v[140:143], v193
	s_ashr_i32 s77, s76, 4
	s_sub_i32 s77, 64, s77
	s_sub_i32 s78, s40, s76
	s_waitcnt lgkmcnt(0)
	s_add_i32 s93, s8, 0x100
	s_mov_b32 m0, s12
	v_add_u32_e32 v164, s93, v231
	v_med3_i32 v164, v164, 0, s40
	v_lshl_or_b32 v164, v164, 7, v220
	global_load_lds_dwordx4 v164, s[20:21]
	s_add_i32 m0, s12, 0x400
	v_add_u32_e32 v165, s93, v232
	v_med3_i32 v165, v165, 0, s40
	v_lshl_or_b32 v165, v165, 7, v221
	global_load_lds_dwordx4 v165, s[20:21]
	s_waitcnt vmcnt(8)
	v_add_u32_e32 v154, s13, v223
	v_add_u32_e32 v155, s13, v224
	ds_read_b128 v[88:91], v154
	ds_read_b128 v[92:95], v155
	v_mfma_f32_16x16x32_bf16 v[36:39], v[202:205], v[80:83], 0
	v_mfma_f32_16x16x32_bf16 v[36:39], v[206:209], v[84:87], v[36:39]
	s_ashr_i32 s78, s78, 4
	s_add_i32 s78, s78, 64
	v_cndmask_b32_e64 v0, v0, v230, s[52:53]
	v_cndmask_b32_e64 v32, v32, v230, s[62:63]
	v_cndmask_b32_e64 v1, v1, v230, s[56:57]
	v_cndmask_b32_e64 v33, v33, v230, s[64:65]
	v_cndmask_b32_e64 v2, v2, v230, s[58:59]
	v_cndmask_b32_e64 v34, v34, v230, s[70:71]
	v_cndmask_b32_e64 v3, v3, v230, s[60:61]
	v_cndmask_b32_e64 v35, v35, v230, s[72:73]
	v_sub_u32_e32 v200, s77, v229
	s_sub_i32 s91, s78, s77
	v_sub_u32_e32 v150, 0, v200
	v_sub_u32_e32 v151, 1, v200
	v_sub_u32_e32 v152, 2, v200
	v_sub_u32_e32 v153, 3, v200
	v_cmp_lt_u32_e64 s[94:95], s91, v150
	v_cmp_lt_u32_e64 s[86:87], s91, v151
	v_cmp_lt_u32_e64 s[0:1], s91, v152
	v_cmp_lt_u32_e64 s[2:3], s91, v153
	v_cndmask_b32_e64 v0, v0, v230, s[94:95]
	v_cndmask_b32_e64 v1, v1, v230, s[86:87]
	v_cndmask_b32_e64 v2, v2, v230, s[0:1]
	v_cndmask_b32_e64 v3, v3, v230, s[2:3]
	v_sub_u32_e32 v150, 16, v200
	v_sub_u32_e32 v151, 17, v200
	v_sub_u32_e32 v152, 18, v200
	v_sub_u32_e32 v153, 19, v200
	s_waitcnt lgkmcnt(0)
	s_add_i32 s93, s8, 0x200
	s_mov_b32 m0, s13
	v_add_u32_e32 v164, s93, v231
	v_med3_i32 v164, v164, 0, s40
	v_lshl_or_b32 v164, v164, 7, v220
	global_load_lds_dwordx4 v164, s[20:21]
	s_add_i32 m0, s13, 0x400
	v_add_u32_e32 v165, s93, v232
	v_med3_i32 v165, v165, 0, s40
	v_lshl_or_b32 v165, v165, 7, v221
	global_load_lds_dwordx4 v165, s[20:21]
	s_waitcnt vmcnt(8)
	v_add_u32_e32 v154, s14, v223
	v_add_u32_e32 v155, s14, v224
	ds_read_b128 v[202:205], v154
	ds_read_b128 v[206:209], v155
	v_mfma_f32_16x16x32_bf16 v[40:43], v[88:91], v[80:83], 0
	v_mfma_f32_16x16x32_bf16 v[40:43], v[92:95], v[84:87], v[40:43]
	v_cmp_lt_u32_e64 s[94:95], s91, v150
	v_cmp_lt_u32_e64 s[86:87], s91, v151
	v_cmp_lt_u32_e64 s[0:1], s91, v152
	v_cmp_lt_u32_e64 s[2:3], s91, v153
	v_cndmask_b32_e64 v4, v4, v230, s[94:95]
	v_cndmask_b32_e64 v5, v5, v230, s[86:87]
	v_cndmask_b32_e64 v6, v6, v230, s[0:1]
	v_cndmask_b32_e64 v7, v7, v230, s[2:3]
	v_sub_u32_e32 v150, 32, v200
	v_sub_u32_e32 v151, 33, v200
	v_sub_u32_e32 v152, 34, v200
	v_sub_u32_e32 v153, 35, v200
	v_cmp_lt_u32_e64 s[94:95], s91, v150
	v_cmp_lt_u32_e64 s[86:87], s91, v151
	v_cmp_lt_u32_e64 s[0:1], s91, v152
	v_cmp_lt_u32_e64 s[2:3], s91, v153
	v_cndmask_b32_e64 v8, v8, v230, s[94:95]
	v_cndmask_b32_e64 v9, v9, v230, s[86:87]
	v_cndmask_b32_e64 v10, v10, v230, s[0:1]
	v_cndmask_b32_e64 v11, v11, v230, s[2:3]
	v_sub_u32_e32 v150, 48, v200
	v_sub_u32_e32 v151, 49, v200
	v_sub_u32_e32 v152, 50, v200
	v_sub_u32_e32 v153, 51, v200
	v_cmp_lt_u32_e64 s[94:95], s91, v150
	v_cmp_lt_u32_e64 s[86:87], s91, v151
	v_cmp_lt_u32_e64 s[0:1], s91, v152
	v_cmp_lt_u32_e64 s[2:3], s91, v153
	s_waitcnt lgkmcnt(0)
	s_add_i32 s93, s8, 0x300
	s_mov_b32 m0, s14
	v_add_u32_e32 v164, s93, v231
	v_med3_i32 v164, v164, 0, s40
	v_lshl_or_b32 v164, v164, 7, v220
	global_load_lds_dwordx4 v164, s[20:21]
	s_add_i32 m0, s14, 0x400
	v_add_u32_e32 v165, s93, v232
	v_med3_i32 v165, v165, 0, s40
	v_lshl_or_b32 v165, v165, 7, v221
	global_load_lds_dwordx4 v165, s[20:21]
	s_waitcnt vmcnt(8)
	v_add_u32_e32 v154, s15, v223
	v_add_u32_e32 v155, s15, v224
	ds_read_b128 v[88:91], v154
	ds_read_b128 v[92:95], v155
	v_mfma_f32_16x16x32_bf16 v[44:47], v[202:205], v[80:83], 0
	v_mfma_f32_16x16x32_bf16 v[44:47], v[206:209], v[84:87], v[44:47]
	v_cndmask_b32_e64 v12, v12, v230, s[94:95]
	v_cndmask_b32_e64 v13, v13, v230, s[86:87]
	v_cndmask_b32_e64 v14, v14, v230, s[0:1]
	v_cndmask_b32_e64 v15, v15, v230, s[2:3]
	v_sub_u32_e32 v150, 64, v200
	v_sub_u32_e32 v151, 0x41, v200
	v_sub_u32_e32 v152, 0x42, v200
	v_sub_u32_e32 v153, 0x43, v200
	v_cmp_lt_u32_e64 s[94:95], s91, v150
	v_cmp_lt_u32_e64 s[86:87], s91, v151
	v_cmp_lt_u32_e64 s[0:1], s91, v152
	v_cmp_lt_u32_e64 s[2:3], s91, v153
	v_cndmask_b32_e64 v16, v16, v230, s[94:95]
	v_cndmask_b32_e64 v17, v17, v230, s[86:87]
	v_cndmask_b32_e64 v18, v18, v230, s[0:1]
	v_cndmask_b32_e64 v19, v19, v230, s[2:3]
	v_sub_u32_e32 v150, 0x50, v200
	v_sub_u32_e32 v151, 0x51, v200
	v_sub_u32_e32 v152, 0x52, v200
	v_sub_u32_e32 v153, 0x53, v200
	v_cmp_lt_u32_e64 s[94:95], s91, v150
	v_cmp_lt_u32_e64 s[86:87], s91, v151
	v_cmp_lt_u32_e64 s[0:1], s91, v152
	v_cmp_lt_u32_e64 s[2:3], s91, v153
	v_cndmask_b32_e64 v20, v20, v230, s[94:95]
	v_cndmask_b32_e64 v21, v21, v230, s[86:87]
	v_cndmask_b32_e64 v22, v22, v230, s[0:1]
	v_cndmask_b32_e64 v23, v23, v230, s[2:3]
	s_waitcnt lgkmcnt(0)
	s_add_i32 s93, s8, 0x400
	s_mov_b32 m0, s15
	v_add_u32_e32 v164, s93, v231
	v_med3_i32 v164, v164, 0, s40
	v_lshl_or_b32 v164, v164, 7, v220
	global_load_lds_dwordx4 v164, s[20:21]
	s_add_i32 m0, s15, 0x400
	v_add_u32_e32 v165, s93, v232
	v_med3_i32 v165, v165, 0, s40
	v_lshl_or_b32 v165, v165, 7, v221
	global_load_lds_dwordx4 v165, s[20:21]
	s_waitcnt vmcnt(8)
	v_add_u32_e32 v154, s16, v223
	v_add_u32_e32 v155, s16, v224
	ds_read_b128 v[202:205], v154
	ds_read_b128 v[206:209], v155
	v_mfma_f32_16x16x32_bf16 v[48:51], v[88:91], v[80:83], 0
	v_mfma_f32_16x16x32_bf16 v[48:51], v[92:95], v[84:87], v[48:51]
	v_sub_u32_e32 v150, 0x60, v200
	v_sub_u32_e32 v151, 0x61, v200
	v_sub_u32_e32 v152, 0x62, v200
	v_sub_u32_e32 v153, 0x63, v200
	v_cmp_lt_u32_e64 s[94:95], s91, v150
	v_cmp_lt_u32_e64 s[86:87], s91, v151
	v_cmp_lt_u32_e64 s[0:1], s91, v152
	v_cmp_lt_u32_e64 s[2:3], s91, v153
	v_cndmask_b32_e64 v24, v24, v230, s[94:95]
	v_cndmask_b32_e64 v25, v25, v230, s[86:87]
	v_cndmask_b32_e64 v26, v26, v230, s[0:1]
	v_cndmask_b32_e64 v27, v27, v230, s[2:3]
	v_sub_u32_e32 v150, 0x70, v200
	v_sub_u32_e32 v151, 0x71, v200
	v_sub_u32_e32 v152, 0x72, v200
	v_sub_u32_e32 v153, 0x73, v200
	v_cmp_lt_u32_e64 s[94:95], s91, v150
	v_cmp_lt_u32_e64 s[86:87], s91, v151
	v_cmp_lt_u32_e64 s[0:1], s91, v152
	v_cmp_lt_u32_e64 s[2:3], s91, v153
	v_cndmask_b32_e64 v28, v28, v230, s[94:95]
	v_cndmask_b32_e64 v29, v29, v230, s[86:87]
	v_cndmask_b32_e64 v30, v30, v230, s[0:1]
	v_cndmask_b32_e64 v31, v31, v230, s[2:3]
	v_sub_u32_e32 v150, 0x80, v200
	v_sub_u32_e32 v151, 0x81, v200
	v_sub_u32_e32 v152, 0x82, v200
	v_sub_u32_e32 v153, 0x83, v200
	s_waitcnt lgkmcnt(0)
	s_add_i32 s93, s76, 0xfffffc00
	s_mov_b32 m0, s16
	v_add_u32_e32 v164, s93, v231
	v_med3_i32 v164, v164, 0, s40
	v_lshl_or_b32 v164, v164, 7, v222
	global_load_lds_dwordx4 v164, s[24:25]
	s_add_i32 m0, s16, 0x400
	v_add_u32_e32 v165, s93, v232
	v_med3_i32 v165, v165, 0, s40
	v_lshl_or_b32 v165, v165, 7, v222
	global_load_lds_dwordx4 v165, s[24:25]
	s_waitcnt vmcnt(8)
	v_add_u32_e32 v154, s12, v223
	v_add_u32_e32 v155, s12, v224
	ds_read_b128 v[88:91], v154
	ds_read_b128 v[92:95], v155
	v_mfma_f32_16x16x32_bf16 v[52:55], v[202:205], v[80:83], 0
	v_mfma_f32_16x16x32_bf16 v[52:55], v[206:209], v[84:87], v[52:55]
	v_cmp_lt_u32_e64 s[94:95], s91, v150
	v_cmp_lt_u32_e64 s[86:87], s91, v151
	v_cmp_lt_u32_e64 s[0:1], s91, v152
	v_cmp_lt_u32_e64 s[2:3], s91, v153
	v_cndmask_b32_e64 v32, v32, v230, s[94:95]
	v_cndmask_b32_e64 v33, v33, v230, s[86:87]
	v_cndmask_b32_e64 v34, v34, v230, s[0:1]
	v_cndmask_b32_e64 v35, v35, v230, s[2:3]
	v_max3_f32 v184, v0, v1, v2
	v_max3_f32 v184, v184, v3, v4
	v_max3_f32 v184, v184, v5, v6
	v_max3_f32 v184, v184, v7, v8
	v_max3_f32 v184, v184, v9, v10
	v_max3_f32 v184, v184, v11, v12
	v_max3_f32 v184, v184, v13, v14
	v_max3_f32 v184, v184, v15, v16
	v_max3_f32 v184, v184, v17, v18
	v_max3_f32 v184, v184, v19, v20
	v_max3_f32 v184, v184, v21, v22
	v_max3_f32 v184, v184, v23, v24
	v_max3_f32 v184, v184, v25, v26
	v_max3_f32 v184, v184, v27, v28
	v_max3_f32 v184, v184, v29, v30
	v_max3_f32 v184, v184, v31, v32
	v_max3_f32 v184, v184, v33, v34
	v_max_f32_e32 v184, v184, v35
	v_mov_b32_e32 v146, v184
	s_nop 1
	v_permlane16_swap_b32_e32 v184, v146
	s_waitcnt lgkmcnt(0)
	s_add_i32 s93, s76, 0xfffffd00
	s_mov_b32 m0, s12
	v_add_u32_e32 v164, s93, v231
	v_med3_i32 v164, v164, 0, s40
	v_lshl_or_b32 v164, v164, 7, v222
	global_load_lds_dwordx4 v164, s[24:25]
	s_add_i32 m0, s12, 0x400
	v_add_u32_e32 v165, s93, v232
	v_med3_i32 v165, v165, 0, s40
	v_lshl_or_b32 v165, v165, 7, v222
	global_load_lds_dwordx4 v165, s[24:25]
	s_waitcnt vmcnt(8)
	v_add_u32_e32 v154, s13, v223
	v_add_u32_e32 v155, s13, v224
	ds_read_b128 v[202:205], v154
	ds_read_b128 v[206:209], v155
	v_mfma_f32_16x16x32_bf16 v[56:59], v[88:91], v[80:83], 0
	v_mfma_f32_16x16x32_bf16 v[56:59], v[92:95], v[84:87], v[56:59]
	v_max_f32_e32 v184, v184, v146
	v_mov_b32_e32 v146, v184
	s_nop 1
	v_permlane32_swap_b32_e32 v184, v146
	v_max_f32_e32 v184, v184, v146
	v_pk_add_f32 v[0:1], v[0:1], v[184:185] op_sel_hi:[1,0] neg_lo:[0,1] neg_hi:[0,1]
	v_pk_add_f32 v[2:3], v[2:3], v[184:185] op_sel_hi:[1,0] neg_lo:[0,1] neg_hi:[0,1]
	v_pk_add_f32 v[4:5], v[4:5], v[184:185] op_sel_hi:[1,0] neg_lo:[0,1] neg_hi:[0,1]
	v_pk_add_f32 v[6:7], v[6:7], v[184:185] op_sel_hi:[1,0] neg_lo:[0,1] neg_hi:[0,1]
	v_exp_f32_e32 v0, v0
	v_exp_f32_e32 v1, v1
	v_exp_f32_e32 v2, v2
	v_exp_f32_e32 v3, v3
	v_pk_add_f32 v[8:9], v[8:9], v[184:185] op_sel_hi:[1,0] neg_lo:[0,1] neg_hi:[0,1]
	v_pk_add_f32 v[10:11], v[10:11], v[184:185] op_sel_hi:[1,0] neg_lo:[0,1] neg_hi:[0,1]
	v_exp_f32_e32 v4, v4
	v_exp_f32_e32 v5, v5
	v_exp_f32_e32 v6, v6
	v_exp_f32_e32 v7, v7
	v_pk_add_f32 v[12:13], v[12:13], v[184:185] op_sel_hi:[1,0] neg_lo:[0,1] neg_hi:[0,1]
	v_pk_add_f32 v[14:15], v[14:15], v[184:185] op_sel_hi:[1,0] neg_lo:[0,1] neg_hi:[0,1]
	v_exp_f32_e32 v8, v8
	v_exp_f32_e32 v9, v9
	v_exp_f32_e32 v10, v10
	v_exp_f32_e32 v11, v11
	v_pk_add_f32 v[16:17], v[16:17], v[184:185] op_sel_hi:[1,0] neg_lo:[0,1] neg_hi:[0,1]
	v_pk_add_f32 v[18:19], v[18:19], v[184:185] op_sel_hi:[1,0] neg_lo:[0,1] neg_hi:[0,1]
	v_exp_f32_e32 v12, v12
	v_exp_f32_e32 v13, v13
	s_waitcnt lgkmcnt(0)
	s_add_i32 s93, s76, 0xfffffe00
	s_mov_b32 m0, s13
	v_add_u32_e32 v164, s93, v231
	v_med3_i32 v164, v164, 0, s40
	v_lshl_or_b32 v164, v164, 7, v222
	global_load_lds_dwordx4 v164, s[24:25]
	s_add_i32 m0, s13, 0x400
	v_add_u32_e32 v165, s93, v232
	v_med3_i32 v165, v165, 0, s40
	v_lshl_or_b32 v165, v165, 7, v222
	global_load_lds_dwordx4 v165, s[24:25]
	s_waitcnt vmcnt(8)
	v_add_u32_e32 v154, s14, v223
	v_add_u32_e32 v155, s14, v224
	ds_read_b128 v[88:91], v154
	ds_read_b128 v[92:95], v155
	v_mfma_f32_16x16x32_bf16 v[60:63], v[202:205], v[80:83], 0
	v_mfma_f32_16x16x32_bf16 v[60:63], v[206:209], v[84:87], v[60:63]
	v_exp_f32_e32 v14, v14
	v_exp_f32_e32 v15, v15
	v_pk_add_f32 v[20:21], v[20:21], v[184:185] op_sel_hi:[1,0] neg_lo:[0,1] neg_hi:[0,1]
	v_pk_add_f32 v[22:23], v[22:23], v[184:185] op_sel_hi:[1,0] neg_lo:[0,1] neg_hi:[0,1]
	v_exp_f32_e32 v16, v16
	v_exp_f32_e32 v17, v17
	v_exp_f32_e32 v18, v18
	v_exp_f32_e32 v19, v19
	v_pk_add_f32 v[24:25], v[24:25], v[184:185] op_sel_hi:[1,0] neg_lo:[0,1] neg_hi:[0,1]
	v_pk_add_f32 v[26:27], v[26:27], v[184:185] op_sel_hi:[1,0] neg_lo:[0,1] neg_hi:[0,1]
	v_exp_f32_e32 v20, v20
	v_exp_f32_e32 v21, v21
	v_exp_f32_e32 v22, v22
	v_exp_f32_e32 v23, v23
	v_pk_add_f32 v[28:29], v[28:29], v[184:185] op_sel_hi:[1,0] neg_lo:[0,1] neg_hi:[0,1]
	v_pk_add_f32 v[30:31], v[30:31], v[184:185] op_sel_hi:[1,0] neg_lo:[0,1] neg_hi:[0,1]
	v_exp_f32_e32 v24, v24
	v_exp_f32_e32 v25, v25
	v_exp_f32_e32 v26, v26
	v_exp_f32_e32 v27, v27
	v_pk_add_f32 v[32:33], v[32:33], v[184:185] op_sel_hi:[1,0] neg_lo:[0,1] neg_hi:[0,1]
	v_pk_add_f32 v[34:35], v[34:35], v[184:185] op_sel_hi:[1,0] neg_lo:[0,1] neg_hi:[0,1]
	v_exp_f32_e32 v28, v28
	v_exp_f32_e32 v29, v29
	v_exp_f32_e32 v30, v30
	v_exp_f32_e32 v31, v31
	v_exp_f32_e32 v32, v32
	v_exp_f32_e32 v33, v33
	s_waitcnt lgkmcnt(0)
	s_add_i32 s93, s76, 0xffffff00
	s_mov_b32 m0, s14
	v_add_u32_e32 v164, s93, v231
	v_med3_i32 v164, v164, 0, s40
	v_lshl_or_b32 v164, v164, 7, v222
	global_load_lds_dwordx4 v164, s[24:25]
	s_add_i32 m0, s14, 0x400
	v_add_u32_e32 v165, s93, v232
	v_med3_i32 v165, v165, 0, s40
	v_lshl_or_b32 v165, v165, 7, v222
	global_load_lds_dwordx4 v165, s[24:25]
	s_waitcnt vmcnt(8)
	v_add_u32_e32 v154, s15, v223
	v_add_u32_e32 v155, s15, v224
	ds_read_b128 v[202:205], v154
	ds_read_b128 v[206:209], v155
	v_mfma_f32_16x16x32_bf16 v[64:67], v[88:91], v[80:83], 0
	v_mfma_f32_16x16x32_bf16 v[64:67], v[92:95], v[84:87], v[64:67]
	v_exp_f32_e32 v34, v34
	v_exp_f32_e32 v35, v35
	s_nop 0
	v_pk_add_f32 v[146:147], v[0:1], v[2:3]
	v_pk_add_f32 v[148:149], v[4:5], v[6:7]
	v_pk_add_f32 v[146:147], v[146:147], v[8:9]
	v_pk_add_f32 v[148:149], v[148:149], v[10:11]
	v_pk_add_f32 v[146:147], v[146:147], v[12:13]
	v_pk_add_f32 v[148:149], v[148:149], v[14:15]
	v_pk_add_f32 v[146:147], v[146:147], v[16:17]
	v_pk_add_f32 v[148:149], v[148:149], v[18:19]
	v_pk_add_f32 v[146:147], v[146:147], v[20:21]
	v_pk_add_f32 v[148:149], v[148:149], v[22:23]
	v_pk_add_f32 v[146:147], v[146:147], v[24:25]
	v_pk_add_f32 v[148:149], v[148:149], v[26:27]
	v_pk_add_f32 v[146:147], v[146:147], v[28:29]
	v_pk_add_f32 v[148:149], v[148:149], v[30:31]
	v_pk_add_f32 v[146:147], v[146:147], v[32:33]
	v_pk_add_f32 v[148:149], v[148:149], v[34:35]
	s_nop 0
	v_pk_add_f32 v[146:147], v[146:147], v[148:149]
	s_nop 0
	v_add_f32_e32 v185, v146, v147
	v_cvt_pk_bf16_f32 v0, v0, v1
	v_cvt_pk_bf16_f32 v1, v2, v3
	v_cvt_pk_bf16_f32 v4, v4, v5
	v_cvt_pk_bf16_f32 v5, v6, v7
	v_cvt_pk_bf16_f32 v8, v8, v9
	s_waitcnt lgkmcnt(0)
	s_add_i32 s93, s76, 0
	s_mov_b32 m0, s15
	v_add_u32_e32 v164, s93, v231
	v_med3_i32 v164, v164, 0, s40
	v_lshl_or_b32 v164, v164, 7, v222
	global_load_lds_dwordx4 v164, s[24:25]
	s_add_i32 m0, s15, 0x400
	v_add_u32_e32 v165, s93, v232
	v_med3_i32 v165, v165, 0, s40
	v_lshl_or_b32 v165, v165, 7, v222
	global_load_lds_dwordx4 v165, s[24:25]
	s_waitcnt vmcnt(8)
	v_add_u32_e32 v154, s16, v225
	v_add_u32_e32 v155, s16, v226
	v_add_u32_e32 v156, s16, v227
	v_add_u32_e32 v157, s16, v228
	ds_read_b64_tr_b16 v[88:89], v154
	ds_read_b64_tr_b16 v[90:91], v155
	ds_read_b64_tr_b16 v[92:93], v156
	ds_read_b64_tr_b16 v[94:95], v157
	v_mfma_f32_16x16x32_bf16 v[68:71], v[202:205], v[80:83], 0
	v_mfma_f32_16x16x32_bf16 v[68:71], v[206:209], v[84:87], v[68:71]
	v_cvt_pk_bf16_f32 v9, v10, v11
	v_cvt_pk_bf16_f32 v12, v12, v13
	v_cvt_pk_bf16_f32 v13, v14, v15
	v_cvt_pk_bf16_f32 v16, v16, v17
	v_cvt_pk_bf16_f32 v17, v18, v19
	v_cvt_pk_bf16_f32 v20, v20, v21
	v_cvt_pk_bf16_f32 v21, v22, v23
	v_cvt_pk_bf16_f32 v24, v24, v25
	v_cvt_pk_bf16_f32 v25, v26, v27
	v_cvt_pk_bf16_f32 v28, v28, v29
	v_cvt_pk_bf16_f32 v29, v30, v31
	v_cvt_pk_bf16_f32 v32, v32, v33
	v_cvt_pk_bf16_f32 v33, v34, v35
	v_mov_b32_e32 v146, v185
	s_nop 1
	v_permlane16_swap_b32_e32 v185, v146
	v_add_f32_e32 v185, v185, v146
	v_mov_b32_e32 v146, v185
	s_nop 1
	v_permlane32_swap_b32_e32 v185, v146
	v_add_f32_e32 v185, v185, v146
	s_waitcnt lgkmcnt(0)
	s_add_i32 s93, s76, 0x100
	s_mov_b32 m0, s16
	v_add_u32_e32 v164, s93, v231
	v_med3_i32 v164, v164, 0, s40
	v_lshl_or_b32 v164, v164, 7, v222
	global_load_lds_dwordx4 v164, s[24:25]
	s_add_i32 m0, s16, 0x400
	v_add_u32_e32 v165, s93, v232
	v_med3_i32 v165, v165, 0, s40
	v_lshl_or_b32 v165, v165, 7, v222
	global_load_lds_dwordx4 v165, s[24:25]
	s_waitcnt vmcnt(8)
	v_add_u32_e32 v154, s12, v225
	v_add_u32_e32 v155, s12, v226
	v_add_u32_e32 v156, s12, v227
	v_add_u32_e32 v157, s12, v228
	ds_read_b64_tr_b16 v[202:203], v154
	ds_read_b64_tr_b16 v[204:205], v155
	ds_read_b64_tr_b16 v[206:207], v156
	ds_read_b64_tr_b16 v[208:209], v157
	v_mfma_f32_16x16x16_bf16 v[96:99], v[88:89], v[0:1], 0
	v_mfma_f32_16x16x16_bf16 v[100:103], v[90:91], v[0:1], 0
	v_mfma_f32_16x16x16_bf16 v[104:107], v[92:93], v[0:1], 0
	v_mfma_f32_16x16x16_bf16 v[108:111], v[94:95], v[0:1], 0
	v_mov_b32_e32 v189, s85
	v_lshl_add_u32 v189, v216, 4, v189
	v_lshrrev_b32_e32 v146, 4, v189
	v_xor_b32_e32 v146, v146, v189
	v_and_b32_e32 v146, 15, v146
	v_lshlrev_b32_e32 v147, 8, v189
	v_or_b32_e32 v148, 0, v217
	v_xor_b32_e32 v148, v148, v146
	v_lshl_add_u32 v195, v148, 4, v147
	v_or_b32_e32 v148, 4, v217
	v_xor_b32_e32 v148, v148, v146
	v_lshl_add_u32 v196, v148, 4, v147
	v_or_b32_e32 v148, 8, v217
	v_xor_b32_e32 v148, v148, v146
	v_lshl_add_u32 v197, v148, 4, v147
	v_or_b32_e32 v148, 12, v217
	v_xor_b32_e32 v148, v148, v146
	v_lshl_add_u32 v198, v148, 4, v147
	v_lshlrev_b32_e32 v199, 3, v189
	v_add_u32_e32 v199, 0x10000, v199
	ds_read_b64 v[182:183], v199
	ds_read_b128 v[166:169], v195
	ds_read_b128 v[170:173], v196
	ds_read_b128 v[174:177], v197
	ds_read_b128 v[178:181], v198
	s_ashr_i32 s77, s8, 4
	s_sub_i32 s77, 64, s77
	s_sub_i32 s78, s40, s8
	s_ashr_i32 s78, s78, 4
	s_add_i32 s78, s78, 64
	v_cndmask_b32_e64 v36, v36, v230, s[52:53]
	s_waitcnt lgkmcnt(0)
	s_add_i32 s93, s76, 0x200
	s_mov_b32 m0, s12
	v_add_u32_e32 v164, s93, v231
	v_med3_i32 v164, v164, 0, s40
	v_lshl_or_b32 v164, v164, 7, v222
	global_load_lds_dwordx4 v164, s[24:25]
	s_add_i32 m0, s12, 0x400
	v_add_u32_e32 v165, s93, v232
	v_med3_i32 v165, v165, 0, s40
	v_lshl_or_b32 v165, v165, 7, v222
	global_load_lds_dwordx4 v165, s[24:25]
	s_waitcnt vmcnt(8)
	v_add_u32_e32 v154, s13, v225
	v_add_u32_e32 v155, s13, v226
	v_add_u32_e32 v156, s13, v227
	v_add_u32_e32 v157, s13, v228
	ds_read_b64_tr_b16 v[88:89], v154
	ds_read_b64_tr_b16 v[90:91], v155
	ds_read_b64_tr_b16 v[92:93], v156
	ds_read_b64_tr_b16 v[94:95], v157
	v_mfma_f32_16x16x16_bf16 v[96:99], v[202:203], v[4:5], v[96:99]
	v_mfma_f32_16x16x16_bf16 v[100:103], v[204:205], v[4:5], v[100:103]
	v_mfma_f32_16x16x16_bf16 v[104:107], v[206:207], v[4:5], v[104:107]
	v_mfma_f32_16x16x16_bf16 v[108:111], v[208:209], v[4:5], v[108:111]
	v_cndmask_b32_e64 v68, v68, v230, s[62:63]
	v_cndmask_b32_e64 v37, v37, v230, s[56:57]
	v_cndmask_b32_e64 v69, v69, v230, s[64:65]
	v_cndmask_b32_e64 v38, v38, v230, s[58:59]
	v_cndmask_b32_e64 v70, v70, v230, s[70:71]
	v_cndmask_b32_e64 v39, v39, v230, s[60:61]
	v_cndmask_b32_e64 v71, v71, v230, s[72:73]
	v_sub_u32_e32 v200, s77, v229
	s_sub_i32 s91, s78, s77
	v_sub_u32_e32 v150, 0, v200
	v_sub_u32_e32 v151, 1, v200
	v_sub_u32_e32 v152, 2, v200
	v_sub_u32_e32 v153, 3, v200
	v_cmp_lt_u32_e64 s[94:95], s91, v150
	v_cmp_lt_u32_e64 s[86:87], s91, v151
	v_cmp_lt_u32_e64 s[0:1], s91, v152
	v_cmp_lt_u32_e64 s[2:3], s91, v153
	v_cndmask_b32_e64 v36, v36, v230, s[94:95]
	v_cndmask_b32_e64 v37, v37, v230, s[86:87]
	v_cndmask_b32_e64 v38, v38, v230, s[0:1]
	v_cndmask_b32_e64 v39, v39, v230, s[2:3]
	v_sub_u32_e32 v150, 16, v200
	v_sub_u32_e32 v151, 17, v200
	v_sub_u32_e32 v152, 18, v200
	v_sub_u32_e32 v153, 19, v200
	v_cmp_lt_u32_e64 s[94:95], s91, v150
	v_cmp_lt_u32_e64 s[86:87], s91, v151
	v_cmp_lt_u32_e64 s[0:1], s91, v152
	v_cmp_lt_u32_e64 s[2:3], s91, v153
	v_cndmask_b32_e64 v40, v40, v230, s[94:95]
	v_cndmask_b32_e64 v41, v41, v230, s[86:87]
	s_waitcnt lgkmcnt(0)
	s_add_i32 s93, s76, 0x300
	s_mov_b32 m0, s13
	v_add_u32_e32 v164, s93, v231
	v_med3_i32 v164, v164, 0, s40
	v_lshl_or_b32 v164, v164, 7, v222
	global_load_lds_dwordx4 v164, s[24:25]
	s_add_i32 m0, s13, 0x400
	v_add_u32_e32 v165, s93, v232
	v_med3_i32 v165, v165, 0, s40
	v_lshl_or_b32 v165, v165, 7, v222
	global_load_lds_dwordx4 v165, s[24:25]
	s_waitcnt vmcnt(8)
	v_add_u32_e32 v154, s14, v225
	v_add_u32_e32 v155, s14, v226
	v_add_u32_e32 v156, s14, v227
	v_add_u32_e32 v157, s14, v228
	ds_read_b64_tr_b16 v[202:203], v154
	ds_read_b64_tr_b16 v[204:205], v155
	ds_read_b64_tr_b16 v[206:207], v156
	ds_read_b64_tr_b16 v[208:209], v157
	v_mfma_f32_16x16x16_bf16 v[96:99], v[88:89], v[8:9], v[96:99]
	v_mfma_f32_16x16x16_bf16 v[100:103], v[90:91], v[8:9], v[100:103]
	v_mfma_f32_16x16x16_bf16 v[104:107], v[92:93], v[8:9], v[104:107]
	v_mfma_f32_16x16x16_bf16 v[108:111], v[94:95], v[8:9], v[108:111]
	v_cndmask_b32_e64 v42, v42, v230, s[0:1]
	v_cndmask_b32_e64 v43, v43, v230, s[2:3]
	v_sub_u32_e32 v150, 32, v200
	v_sub_u32_e32 v151, 33, v200
	v_sub_u32_e32 v152, 34, v200
	v_sub_u32_e32 v153, 35, v200
	v_cmp_lt_u32_e64 s[94:95], s91, v150
	v_cmp_lt_u32_e64 s[86:87], s91, v151
	v_cmp_lt_u32_e64 s[0:1], s91, v152
	v_cmp_lt_u32_e64 s[2:3], s91, v153
	v_cndmask_b32_e64 v44, v44, v230, s[94:95]
	v_cndmask_b32_e64 v45, v45, v230, s[86:87]
	v_cndmask_b32_e64 v46, v46, v230, s[0:1]
	v_cndmask_b32_e64 v47, v47, v230, s[2:3]
	v_sub_u32_e32 v150, 48, v200
	v_sub_u32_e32 v151, 49, v200
	v_sub_u32_e32 v152, 50, v200
	v_sub_u32_e32 v153, 51, v200
	v_cmp_lt_u32_e64 s[94:95], s91, v150
	v_cmp_lt_u32_e64 s[86:87], s91, v151
	v_cmp_lt_u32_e64 s[0:1], s91, v152
	v_cmp_lt_u32_e64 s[2:3], s91, v153
	v_cndmask_b32_e64 v48, v48, v230, s[94:95]
	v_cndmask_b32_e64 v49, v49, v230, s[86:87]
	v_cndmask_b32_e64 v50, v50, v230, s[0:1]
	v_cndmask_b32_e64 v51, v51, v230, s[2:3]
	v_sub_u32_e32 v150, 64, v200
	v_sub_u32_e32 v151, 0x41, v200
	v_sub_u32_e32 v152, 0x42, v200
	v_sub_u32_e32 v153, 0x43, v200
	v_cmp_lt_u32_e64 s[94:95], s91, v150
	s_waitcnt lgkmcnt(0)
	s_add_i32 s93, s76, 0x400
	s_mov_b32 m0, s14
	v_add_u32_e32 v164, s93, v231
	v_med3_i32 v164, v164, 0, s40
	v_lshl_or_b32 v164, v164, 7, v222
	global_load_lds_dwordx4 v164, s[24:25]
	s_add_i32 m0, s14, 0x400
	v_add_u32_e32 v165, s93, v232
	v_med3_i32 v165, v165, 0, s40
	v_lshl_or_b32 v165, v165, 7, v222
	global_load_lds_dwordx4 v165, s[24:25]
	s_waitcnt vmcnt(8)
	v_add_u32_e32 v154, s15, v225
	v_add_u32_e32 v155, s15, v226
	v_add_u32_e32 v156, s15, v227
	v_add_u32_e32 v157, s15, v228
	ds_read_b64_tr_b16 v[88:89], v154
	ds_read_b64_tr_b16 v[90:91], v155
	ds_read_b64_tr_b16 v[92:93], v156
	ds_read_b64_tr_b16 v[94:95], v157
	v_mfma_f32_16x16x16_bf16 v[96:99], v[202:203], v[12:13], v[96:99]
	v_mfma_f32_16x16x16_bf16 v[100:103], v[204:205], v[12:13], v[100:103]
	v_mfma_f32_16x16x16_bf16 v[104:107], v[206:207], v[12:13], v[104:107]
	v_mfma_f32_16x16x16_bf16 v[108:111], v[208:209], v[12:13], v[108:111]
	v_cmp_lt_u32_e64 s[86:87], s91, v151
	v_cmp_lt_u32_e64 s[0:1], s91, v152
	v_cmp_lt_u32_e64 s[2:3], s91, v153
	v_cndmask_b32_e64 v52, v52, v230, s[94:95]
	v_cndmask_b32_e64 v53, v53, v230, s[86:87]
	v_cndmask_b32_e64 v54, v54, v230, s[0:1]
	v_cndmask_b32_e64 v55, v55, v230, s[2:3]
	v_sub_u32_e32 v150, 0x50, v200
	v_sub_u32_e32 v151, 0x51, v200
	v_sub_u32_e32 v152, 0x52, v200
	v_sub_u32_e32 v153, 0x53, v200
	v_cmp_lt_u32_e64 s[94:95], s91, v150
	v_cmp_lt_u32_e64 s[86:87], s91, v151
	v_cmp_lt_u32_e64 s[0:1], s91, v152
	v_cmp_lt_u32_e64 s[2:3], s91, v153
	v_cndmask_b32_e64 v56, v56, v230, s[94:95]
	v_cndmask_b32_e64 v57, v57, v230, s[86:87]
	v_cndmask_b32_e64 v58, v58, v230, s[0:1]
	v_cndmask_b32_e64 v59, v59, v230, s[2:3]
	v_sub_u32_e32 v150, 0x60, v200
	v_sub_u32_e32 v151, 0x61, v200
	v_sub_u32_e32 v152, 0x62, v200
	v_sub_u32_e32 v153, 0x63, v200
	v_cmp_lt_u32_e64 s[94:95], s91, v150
	v_cmp_lt_u32_e64 s[86:87], s91, v151
	v_cmp_lt_u32_e64 s[0:1], s91, v152
	v_cmp_lt_u32_e64 s[2:3], s91, v153
	v_cndmask_b32_e64 v60, v60, v230, s[94:95]
	v_cndmask_b32_e64 v61, v61, v230, s[86:87]
	v_cndmask_b32_e64 v62, v62, v230, s[0:1]
	v_cndmask_b32_e64 v63, v63, v230, s[2:3]
	s_waitcnt lgkmcnt(0)
	s_add_i32 s93, s8, 0xfffffc00
	s_mov_b32 m0, s15
	v_add_u32_e32 v164, s93, v231
	v_med3_i32 v164, v164, 0, s40
	v_lshl_or_b32 v164, v164, 7, v222
	global_load_lds_dwordx4 v164, s[24:25]
	s_add_i32 m0, s15, 0x400
	v_add_u32_e32 v165, s93, v232
	v_med3_i32 v165, v165, 0, s40
	v_lshl_or_b32 v165, v165, 7, v222
	global_load_lds_dwordx4 v165, s[24:25]
	s_waitcnt vmcnt(8)
	v_add_u32_e32 v154, s16, v225
	v_add_u32_e32 v155, s16, v226
	v_add_u32_e32 v156, s16, v227
	v_add_u32_e32 v157, s16, v228
	ds_read_b64_tr_b16 v[202:203], v154
	ds_read_b64_tr_b16 v[204:205], v155
	ds_read_b64_tr_b16 v[206:207], v156
	ds_read_b64_tr_b16 v[208:209], v157
	v_mfma_f32_16x16x16_bf16 v[96:99], v[88:89], v[16:17], v[96:99]
	v_mfma_f32_16x16x16_bf16 v[100:103], v[90:91], v[16:17], v[100:103]
	v_mfma_f32_16x16x16_bf16 v[104:107], v[92:93], v[16:17], v[104:107]
	v_mfma_f32_16x16x16_bf16 v[108:111], v[94:95], v[16:17], v[108:111]
	v_sub_u32_e32 v150, 0x70, v200
	v_sub_u32_e32 v151, 0x71, v200
	v_sub_u32_e32 v152, 0x72, v200
	v_sub_u32_e32 v153, 0x73, v200
	v_cmp_lt_u32_e64 s[94:95], s91, v150
	v_cmp_lt_u32_e64 s[86:87], s91, v151
	v_cmp_lt_u32_e64 s[0:1], s91, v152
	v_cmp_lt_u32_e64 s[2:3], s91, v153
	v_cndmask_b32_e64 v64, v64, v230, s[94:95]
	v_cndmask_b32_e64 v65, v65, v230, s[86:87]
	v_cndmask_b32_e64 v66, v66, v230, s[0:1]
	v_cndmask_b32_e64 v67, v67, v230, s[2:3]
	v_sub_u32_e32 v150, 0x80, v200
	v_sub_u32_e32 v151, 0x81, v200
	v_sub_u32_e32 v152, 0x82, v200
	v_sub_u32_e32 v153, 0x83, v200
	v_cmp_lt_u32_e64 s[94:95], s91, v150
	v_cmp_lt_u32_e64 s[86:87], s91, v151
	v_cmp_lt_u32_e64 s[0:1], s91, v152
	v_cmp_lt_u32_e64 s[2:3], s91, v153
	v_cndmask_b32_e64 v68, v68, v230, s[94:95]
	v_cndmask_b32_e64 v69, v69, v230, s[86:87]
	v_cndmask_b32_e64 v70, v70, v230, s[0:1]
	v_cndmask_b32_e64 v71, v71, v230, s[2:3]
	v_max3_f32 v186, v36, v37, v38
	v_max3_f32 v186, v186, v39, v40
	v_max3_f32 v186, v186, v41, v42
	v_max3_f32 v186, v186, v43, v44
	v_max3_f32 v186, v186, v45, v46
	v_max3_f32 v186, v186, v47, v48
	v_max3_f32 v186, v186, v49, v50
	s_waitcnt lgkmcnt(0)
	s_add_i32 s93, s8, 0xfffffd00
	s_mov_b32 m0, s16
	v_add_u32_e32 v164, s93, v231
	v_med3_i32 v164, v164, 0, s40
	v_lshl_or_b32 v164, v164, 7, v222
	global_load_lds_dwordx4 v164, s[24:25]
	s_add_i32 m0, s16, 0x400
	v_add_u32_e32 v165, s93, v232
	v_med3_i32 v165, v165, 0, s40
	v_lshl_or_b32 v165, v165, 7, v222
	global_load_lds_dwordx4 v165, s[24:25]
	s_waitcnt vmcnt(8)
	v_add_u32_e32 v154, s12, v225
	v_add_u32_e32 v155, s12, v226
	v_add_u32_e32 v156, s12, v227
	v_add_u32_e32 v157, s12, v228
	ds_read_b64_tr_b16 v[88:89], v154
	ds_read_b64_tr_b16 v[90:91], v155
	ds_read_b64_tr_b16 v[92:93], v156
	ds_read_b64_tr_b16 v[94:95], v157
	v_mfma_f32_16x16x16_bf16 v[96:99], v[202:203], v[20:21], v[96:99]
	v_mfma_f32_16x16x16_bf16 v[100:103], v[204:205], v[20:21], v[100:103]
	v_mfma_f32_16x16x16_bf16 v[104:107], v[206:207], v[20:21], v[104:107]
	v_mfma_f32_16x16x16_bf16 v[108:111], v[208:209], v[20:21], v[108:111]
	v_max3_f32 v186, v186, v51, v52
	v_max3_f32 v186, v186, v53, v54
	v_max3_f32 v186, v186, v55, v56
	v_max3_f32 v186, v186, v57, v58
	v_max3_f32 v186, v186, v59, v60
	v_max3_f32 v186, v186, v61, v62
	v_max3_f32 v186, v186, v63, v64
	v_max3_f32 v186, v186, v65, v66
	v_max3_f32 v186, v186, v67, v68
	v_max3_f32 v186, v186, v69, v70
	v_max_f32_e32 v186, v186, v71
	v_mov_b32_e32 v146, v186
	s_nop 1
	v_permlane16_swap_b32_e32 v186, v146
	v_max_f32_e32 v186, v186, v146
	v_mov_b32_e32 v146, v186
	s_nop 1
	v_permlane32_swap_b32_e32 v186, v146
	v_max_f32_e32 v186, v186, v146
	v_pk_add_f32 v[36:37], v[36:37], v[186:187] op_sel_hi:[1,0] neg_lo:[0,1] neg_hi:[0,1]
	v_pk_add_f32 v[38:39], v[38:39], v[186:187] op_sel_hi:[1,0] neg_lo:[0,1] neg_hi:[0,1]
	v_pk_add_f32 v[40:41], v[40:41], v[186:187] op_sel_hi:[1,0] neg_lo:[0,1] neg_hi:[0,1]
	v_pk_add_f32 v[42:43], v[42:43], v[186:187] op_sel_hi:[1,0] neg_lo:[0,1] neg_hi:[0,1]
	v_exp_f32_e32 v36, v36
	v_exp_f32_e32 v37, v37
	v_exp_f32_e32 v38, v38
	v_exp_f32_e32 v39, v39
	v_pk_add_f32 v[44:45], v[44:45], v[186:187] op_sel_hi:[1,0] neg_lo:[0,1] neg_hi:[0,1]
	v_pk_add_f32 v[46:47], v[46:47], v[186:187] op_sel_hi:[1,0] neg_lo:[0,1] neg_hi:[0,1]
	v_exp_f32_e32 v40, v40
	v_exp_f32_e32 v41, v41
	v_exp_f32_e32 v42, v42
	v_exp_f32_e32 v43, v43
	s_waitcnt lgkmcnt(0)
	s_add_i32 s93, s8, 0xfffffe00
	s_mov_b32 m0, s12
	v_add_u32_e32 v164, s93, v231
	v_med3_i32 v164, v164, 0, s40
	v_lshl_or_b32 v164, v164, 7, v222
	global_load_lds_dwordx4 v164, s[24:25]
	s_add_i32 m0, s12, 0x400
	v_add_u32_e32 v165, s93, v232
	v_med3_i32 v165, v165, 0, s40
	v_lshl_or_b32 v165, v165, 7, v222
	global_load_lds_dwordx4 v165, s[24:25]
	s_waitcnt vmcnt(8)
	v_add_u32_e32 v154, s13, v225
	v_add_u32_e32 v155, s13, v226
	v_add_u32_e32 v156, s13, v227
	v_add_u32_e32 v157, s13, v228
	ds_read_b64_tr_b16 v[202:203], v154
	ds_read_b64_tr_b16 v[204:205], v155
	ds_read_b64_tr_b16 v[206:207], v156
	ds_read_b64_tr_b16 v[208:209], v157
	v_mfma_f32_16x16x16_bf16 v[96:99], v[88:89], v[24:25], v[96:99]
	v_mfma_f32_16x16x16_bf16 v[100:103], v[90:91], v[24:25], v[100:103]
	v_mfma_f32_16x16x16_bf16 v[104:107], v[92:93], v[24:25], v[104:107]
	v_mfma_f32_16x16x16_bf16 v[108:111], v[94:95], v[24:25], v[108:111]
	v_pk_add_f32 v[48:49], v[48:49], v[186:187] op_sel_hi:[1,0] neg_lo:[0,1] neg_hi:[0,1]
	v_pk_add_f32 v[50:51], v[50:51], v[186:187] op_sel_hi:[1,0] neg_lo:[0,1] neg_hi:[0,1]
	v_exp_f32_e32 v44, v44
	v_exp_f32_e32 v45, v45
	v_exp_f32_e32 v46, v46
	v_exp_f32_e32 v47, v47
	v_pk_add_f32 v[52:53], v[52:53], v[186:187] op_sel_hi:[1,0] neg_lo:[0,1] neg_hi:[0,1]
	v_pk_add_f32 v[54:55], v[54:55], v[186:187] op_sel_hi:[1,0] neg_lo:[0,1] neg_hi:[0,1]
	v_exp_f32_e32 v48, v48
	v_exp_f32_e32 v49, v49
	v_exp_f32_e32 v50, v50
	v_exp_f32_e32 v51, v51
	v_pk_add_f32 v[56:57], v[56:57], v[186:187] op_sel_hi:[1,0] neg_lo:[0,1] neg_hi:[0,1]
	v_pk_add_f32 v[58:59], v[58:59], v[186:187] op_sel_hi:[1,0] neg_lo:[0,1] neg_hi:[0,1]
	v_exp_f32_e32 v52, v52
	v_exp_f32_e32 v53, v53
	v_exp_f32_e32 v54, v54
	v_exp_f32_e32 v55, v55
	v_pk_add_f32 v[60:61], v[60:61], v[186:187] op_sel_hi:[1,0] neg_lo:[0,1] neg_hi:[0,1]
	v_pk_add_f32 v[62:63], v[62:63], v[186:187] op_sel_hi:[1,0] neg_lo:[0,1] neg_hi:[0,1]
	v_exp_f32_e32 v56, v56
	v_exp_f32_e32 v57, v57
	v_exp_f32_e32 v58, v58
	v_exp_f32_e32 v59, v59
	v_pk_add_f32 v[64:65], v[64:65], v[186:187] op_sel_hi:[1,0] neg_lo:[0,1] neg_hi:[0,1]
	v_pk_add_f32 v[66:67], v[66:67], v[186:187] op_sel_hi:[1,0] neg_lo:[0,1] neg_hi:[0,1]
	v_exp_f32_e32 v60, v60
	v_exp_f32_e32 v61, v61
	v_exp_f32_e32 v62, v62
	v_exp_f32_e32 v63, v63
	v_pk_add_f32 v[68:69], v[68:69], v[186:187] op_sel_hi:[1,0] neg_lo:[0,1] neg_hi:[0,1]
	s_waitcnt lgkmcnt(0)
	s_add_i32 s93, s8, 0xffffff00
	s_mov_b32 m0, s13
	v_add_u32_e32 v164, s93, v231
	v_med3_i32 v164, v164, 0, s40
	v_lshl_or_b32 v164, v164, 7, v222
	global_load_lds_dwordx4 v164, s[24:25]
	s_add_i32 m0, s13, 0x400
	v_add_u32_e32 v165, s93, v232
	v_med3_i32 v165, v165, 0, s40
	v_lshl_or_b32 v165, v165, 7, v222
	global_load_lds_dwordx4 v165, s[24:25]
	s_waitcnt vmcnt(8)
	v_add_u32_e32 v154, s14, v225
	v_add_u32_e32 v155, s14, v226
	v_add_u32_e32 v156, s14, v227
	v_add_u32_e32 v157, s14, v228
	ds_read_b64_tr_b16 v[88:89], v154
	ds_read_b64_tr_b16 v[90:91], v155
	ds_read_b64_tr_b16 v[92:93], v156
	ds_read_b64_tr_b16 v[94:95], v157
	v_mfma_f32_16x16x16_bf16 v[96:99], v[202:203], v[28:29], v[96:99]
	v_mfma_f32_16x16x16_bf16 v[100:103], v[204:205], v[28:29], v[100:103]
	v_mfma_f32_16x16x16_bf16 v[104:107], v[206:207], v[28:29], v[104:107]
	v_mfma_f32_16x16x16_bf16 v[108:111], v[208:209], v[28:29], v[108:111]
	v_pk_add_f32 v[70:71], v[70:71], v[186:187] op_sel_hi:[1,0] neg_lo:[0,1] neg_hi:[0,1]
	v_exp_f32_e32 v64, v64
	v_exp_f32_e32 v65, v65
	v_exp_f32_e32 v66, v66
	v_exp_f32_e32 v67, v67
	v_exp_f32_e32 v68, v68
	v_exp_f32_e32 v69, v69
	v_exp_f32_e32 v70, v70
	v_exp_f32_e32 v71, v71
	s_nop 0
	v_pk_add_f32 v[146:147], v[36:37], v[38:39]
	v_pk_add_f32 v[148:149], v[40:41], v[42:43]
	v_pk_add_f32 v[146:147], v[146:147], v[44:45]
	v_pk_add_f32 v[148:149], v[148:149], v[46:47]
	v_pk_add_f32 v[146:147], v[146:147], v[48:49]
	v_pk_add_f32 v[148:149], v[148:149], v[50:51]
	v_pk_add_f32 v[146:147], v[146:147], v[52:53]
	v_pk_add_f32 v[148:149], v[148:149], v[54:55]
	v_pk_add_f32 v[146:147], v[146:147], v[56:57]
	v_pk_add_f32 v[148:149], v[148:149], v[58:59]
	v_pk_add_f32 v[146:147], v[146:147], v[60:61]
	v_pk_add_f32 v[148:149], v[148:149], v[62:63]
	v_pk_add_f32 v[146:147], v[146:147], v[64:65]
	v_pk_add_f32 v[148:149], v[148:149], v[66:67]
	v_pk_add_f32 v[146:147], v[146:147], v[68:69]
	v_pk_add_f32 v[148:149], v[148:149], v[70:71]
	s_nop 0
	v_pk_add_f32 v[146:147], v[146:147], v[148:149]
	s_nop 0
	v_add_f32_e32 v187, v146, v147
	v_cvt_pk_bf16_f32 v36, v36, v37
	s_waitcnt lgkmcnt(0)
	s_add_i32 s93, s8, 0
	s_mov_b32 m0, s14
	v_add_u32_e32 v164, s93, v231
	v_med3_i32 v164, v164, 0, s40
	v_lshl_or_b32 v164, v164, 7, v222
	global_load_lds_dwordx4 v164, s[24:25]
	s_add_i32 m0, s14, 0x400
	v_add_u32_e32 v165, s93, v232
	v_med3_i32 v165, v165, 0, s40
	v_lshl_or_b32 v165, v165, 7, v222
	global_load_lds_dwordx4 v165, s[24:25]
	s_waitcnt vmcnt(8)
	v_add_u32_e32 v72, s15, v225
	v_add_u32_e32 v73, s15, v226
	v_add_u32_e32 v74, s15, v227
	v_add_u32_e32 v75, s15, v228
	ds_read_b64_tr_b16 v[202:203], v72
	ds_read_b64_tr_b16 v[204:205], v73
	ds_read_b64_tr_b16 v[206:207], v74
	ds_read_b64_tr_b16 v[208:209], v75
	v_mfma_f32_16x16x16_bf16 v[96:99], v[88:89], v[32:33], v[96:99]
	v_mfma_f32_16x16x16_bf16 v[100:103], v[90:91], v[32:33], v[100:103]
	v_mfma_f32_16x16x16_bf16 v[104:107], v[92:93], v[32:33], v[104:107]
	v_mfma_f32_16x16x16_bf16 v[108:111], v[94:95], v[32:33], v[108:111]
	v_cvt_pk_bf16_f32 v37, v38, v39
	v_cvt_pk_bf16_f32 v40, v40, v41
	v_cvt_pk_bf16_f32 v41, v42, v43
	v_cvt_pk_bf16_f32 v44, v44, v45
	v_cvt_pk_bf16_f32 v45, v46, v47
	v_cvt_pk_bf16_f32 v48, v48, v49
	v_cvt_pk_bf16_f32 v49, v50, v51
	v_cvt_pk_bf16_f32 v52, v52, v53
	v_cvt_pk_bf16_f32 v53, v54, v55
	v_cvt_pk_bf16_f32 v56, v56, v57
	v_cvt_pk_bf16_f32 v57, v58, v59
	v_cvt_pk_bf16_f32 v60, v60, v61
	v_cvt_pk_bf16_f32 v61, v62, v63
	v_cvt_pk_bf16_f32 v64, v64, v65
	v_cvt_pk_bf16_f32 v65, v66, v67
	v_cvt_pk_bf16_f32 v68, v68, v69
	v_cvt_pk_bf16_f32 v69, v70, v71
	v_mov_b32_e32 v146, v187
	s_nop 1
	v_permlane16_swap_b32_e32 v187, v146
	v_add_f32_e32 v187, v187, v146
	v_mov_b32_e32 v146, v187
	s_nop 1
	v_permlane32_swap_b32_e32 v187, v146
	v_add_f32_e32 v187, v187, v146
	s_waitcnt lgkmcnt(0)
	s_add_i32 s93, s8, 0x100
	s_mov_b32 m0, s15
	v_add_u32_e32 v164, s93, v231
	v_med3_i32 v164, v164, 0, s40
	v_lshl_or_b32 v164, v164, 7, v222
	global_load_lds_dwordx4 v164, s[24:25]
	s_add_i32 m0, s15, 0x400
	v_add_u32_e32 v165, s93, v232
	v_med3_i32 v165, v165, 0, s40
	v_lshl_or_b32 v165, v165, 7, v222
	global_load_lds_dwordx4 v165, s[24:25]
	s_waitcnt vmcnt(8)
	v_add_u32_e32 v72, s16, v225
	v_add_u32_e32 v73, s16, v226
	v_add_u32_e32 v74, s16, v227
	v_add_u32_e32 v75, s16, v228
	ds_read_b64_tr_b16 v[88:89], v72
	ds_read_b64_tr_b16 v[90:91], v73
	ds_read_b64_tr_b16 v[92:93], v74
	ds_read_b64_tr_b16 v[94:95], v75
	v_mfma_f32_16x16x16_bf16 v[112:115], v[202:203], v[36:37], 0
	v_mfma_f32_16x16x16_bf16 v[116:119], v[204:205], v[36:37], 0
	v_mfma_f32_16x16x16_bf16 v[120:123], v[206:207], v[36:37], 0
	v_mfma_f32_16x16x16_bf16 v[124:127], v[208:209], v[36:37], 0
	s_waitcnt lgkmcnt(0)
	v_max_f32_e32 v146, v144, v184
	v_sub_f32_e32 v148, v144, v146
	v_sub_f32_e32 v150, v184, v146
	v_exp_f32_e32 v148, v148
	v_exp_f32_e32 v150, v150
	v_mov_b32_e32 v184, v146
	v_mul_f32_e32 v185, v185, v150
	v_fmac_f32_e32 v185, v145, v148
	v_pk_mul_f32 v[96:97], v[150:151], v[96:97] op_sel_hi:[0,1]
	v_pk_mul_f32 v[98:99], v[150:151], v[98:99] op_sel_hi:[0,1]
	v_pk_mul_f32 v[100:101], v[150:151], v[100:101] op_sel_hi:[0,1]
	s_waitcnt lgkmcnt(0)
	s_add_i32 s93, s8, 0x200
	s_mov_b32 m0, s16
	v_add_u32_e32 v164, s93, v231
	v_med3_i32 v164, v164, 0, s40
	v_lshl_or_b32 v164, v164, 7, v222
	global_load_lds_dwordx4 v164, s[24:25]
	s_add_i32 m0, s16, 0x400
	v_add_u32_e32 v165, s93, v232
	v_med3_i32 v165, v165, 0, s40
	v_lshl_or_b32 v165, v165, 7, v222
	global_load_lds_dwordx4 v165, s[24:25]
	s_waitcnt vmcnt(8)
	v_add_u32_e32 v72, s12, v225
	v_add_u32_e32 v73, s12, v226
	v_add_u32_e32 v74, s12, v227
	v_add_u32_e32 v75, s12, v228
	ds_read_b64_tr_b16 v[202:203], v72
	ds_read_b64_tr_b16 v[204:205], v73
	ds_read_b64_tr_b16 v[206:207], v74
	ds_read_b64_tr_b16 v[208:209], v75
	v_mfma_f32_16x16x16_bf16 v[112:115], v[88:89], v[40:41], v[112:115]
	v_mfma_f32_16x16x16_bf16 v[116:119], v[90:91], v[40:41], v[116:119]
	v_mfma_f32_16x16x16_bf16 v[120:123], v[92:93], v[40:41], v[120:123]
	v_mfma_f32_16x16x16_bf16 v[124:127], v[94:95], v[40:41], v[124:127]
	v_pk_mul_f32 v[102:103], v[150:151], v[102:103] op_sel_hi:[0,1]
	v_pk_mul_f32 v[104:105], v[150:151], v[104:105] op_sel_hi:[0,1]
	v_pk_mul_f32 v[106:107], v[150:151], v[106:107] op_sel_hi:[0,1]
	v_pk_mul_f32 v[108:109], v[150:151], v[108:109] op_sel_hi:[0,1]
	v_pk_mul_f32 v[110:111], v[150:151], v[110:111] op_sel_hi:[0,1]
	v_pk_fma_f32 v[96:97], v[148:149], v[128:129], v[96:97] op_sel_hi:[0,1,1]
	v_pk_fma_f32 v[98:99], v[148:149], v[130:131], v[98:99] op_sel_hi:[0,1,1]
	v_pk_fma_f32 v[100:101], v[148:149], v[132:133], v[100:101] op_sel_hi:[0,1,1]
	v_pk_fma_f32 v[102:103], v[148:149], v[134:135], v[102:103] op_sel_hi:[0,1,1]
	v_pk_fma_f32 v[104:105], v[148:149], v[136:137], v[104:105] op_sel_hi:[0,1,1]
	v_pk_fma_f32 v[106:107], v[148:149], v[138:139], v[106:107] op_sel_hi:[0,1,1]
	v_pk_fma_f32 v[108:109], v[148:149], v[140:141], v[108:109] op_sel_hi:[0,1,1]
	s_waitcnt lgkmcnt(0)
	s_add_i32 s93, s8, 0x300
	s_mov_b32 m0, s12
	v_add_u32_e32 v164, s93, v231
	v_med3_i32 v164, v164, 0, s40
	v_lshl_or_b32 v164, v164, 7, v222
	global_load_lds_dwordx4 v164, s[24:25]
	s_add_i32 m0, s12, 0x400
	v_add_u32_e32 v165, s93, v232
	v_med3_i32 v165, v165, 0, s40
	v_lshl_or_b32 v165, v165, 7, v222
	global_load_lds_dwordx4 v165, s[24:25]
	s_waitcnt vmcnt(8)
	v_add_u32_e32 v72, s13, v225
	v_add_u32_e32 v73, s13, v226
	v_add_u32_e32 v74, s13, v227
	v_add_u32_e32 v75, s13, v228
	ds_read_b64_tr_b16 v[88:89], v72
	ds_read_b64_tr_b16 v[90:91], v73
	ds_read_b64_tr_b16 v[92:93], v74
	ds_read_b64_tr_b16 v[94:95], v75
	v_mfma_f32_16x16x16_bf16 v[112:115], v[202:203], v[44:45], v[112:115]
	v_mfma_f32_16x16x16_bf16 v[116:119], v[204:205], v[44:45], v[116:119]
	v_mfma_f32_16x16x16_bf16 v[120:123], v[206:207], v[44:45], v[120:123]
	v_mfma_f32_16x16x16_bf16 v[124:127], v[208:209], v[44:45], v[124:127]
	v_pk_fma_f32 v[110:111], v[148:149], v[142:143], v[110:111] op_sel_hi:[0,1,1]
	v_div_scale_f32 v147, s[94:95], v185, v185, 1.0
	v_rcp_f32_e32 v148, v147
	v_div_scale_f32 v149, vcc, 1.0, v185, 1.0
	v_fma_f32 v150, -v147, v148, 1.0
	v_fmac_f32_e32 v148, v150, v148
	v_mul_f32_e32 v150, v149, v148
	v_fma_f32 v151, -v147, v150, v149
	v_fmac_f32_e32 v150, v151, v148
	v_fma_f32 v147, -v147, v150, v149
	s_nop 1
	v_div_fmas_f32 v147, v147, v148, v150
	s_waitcnt lgkmcnt(0)
	s_add_i32 s93, s8, 0x400
	s_mov_b32 m0, s13
	v_add_u32_e32 v164, s93, v231
	v_med3_i32 v164, v164, 0, s40
	v_lshl_or_b32 v164, v164, 7, v222
	global_load_lds_dwordx4 v164, s[24:25]
	s_add_i32 m0, s13, 0x400
	v_add_u32_e32 v165, s93, v232
	v_med3_i32 v165, v165, 0, s40
	v_lshl_or_b32 v165, v165, 7, v222
	global_load_lds_dwordx4 v165, s[24:25]
	s_waitcnt vmcnt(8)
	v_add_u32_e32 v72, s14, v225
	v_add_u32_e32 v73, s14, v226
	v_add_u32_e32 v74, s14, v227
	v_add_u32_e32 v75, s14, v228
	ds_read_b64_tr_b16 v[202:203], v72
	ds_read_b64_tr_b16 v[204:205], v73
	ds_read_b64_tr_b16 v[206:207], v74
	ds_read_b64_tr_b16 v[208:209], v75
	v_mfma_f32_16x16x16_bf16 v[112:115], v[88:89], v[48:49], v[112:115]
	v_mfma_f32_16x16x16_bf16 v[116:119], v[90:91], v[48:49], v[116:119]
	v_mfma_f32_16x16x16_bf16 v[120:123], v[92:93], v[48:49], v[120:123]
	v_mfma_f32_16x16x16_bf16 v[124:127], v[94:95], v[48:49], v[124:127]
	v_div_fixup_f32 v152, v147, v185, 1.0
	v_pk_mul_f32 v[96:97], v[152:153], v[96:97] op_sel_hi:[0,1]
	v_pk_mul_f32 v[98:99], v[152:153], v[98:99] op_sel_hi:[0,1]
	v_pk_mul_f32 v[100:101], v[152:153], v[100:101] op_sel_hi:[0,1]
	v_pk_mul_f32 v[102:103], v[152:153], v[102:103] op_sel_hi:[0,1]
	v_pk_mul_f32 v[104:105], v[152:153], v[104:105] op_sel_hi:[0,1]
	v_pk_mul_f32 v[106:107], v[152:153], v[106:107] op_sel_hi:[0,1]
	v_pk_mul_f32 v[108:109], v[152:153], v[108:109] op_sel_hi:[0,1]
	v_pk_mul_f32 v[110:111], v[152:153], v[110:111] op_sel_hi:[0,1]
	v_mul_f32_e32 v155, v97, v97
	v_mul_f32_e32 v156, v99, v99
	v_fmac_f32_e32 v155, v96, v96
	s_waitcnt lgkmcnt(0)
	s_add_i32 s93, s79, 0
	s_mov_b32 m0, s14
	v_add_u32_e32 v164, s93, v162
	v_lshl_or_b32 v164, v164, 7, v220
	global_load_lds_dwordx4 v164, s[30:31]
	s_add_i32 m0, s14, 0x400
	v_add_u32_e32 v165, s93, v163
	v_lshl_or_b32 v165, v165, 7, v221
	global_load_lds_dwordx4 v165, s[30:31]
	s_waitcnt vmcnt(8)
	v_add_u32_e32 v72, s15, v225
	v_add_u32_e32 v73, s15, v226
	v_add_u32_e32 v74, s15, v227
	v_add_u32_e32 v75, s15, v228
	ds_read_b64_tr_b16 v[88:89], v72
	ds_read_b64_tr_b16 v[90:91], v73
	ds_read_b64_tr_b16 v[92:93], v74
	ds_read_b64_tr_b16 v[94:95], v75
	v_mfma_f32_16x16x16_bf16 v[112:115], v[202:203], v[52:53], v[112:115]
	v_mfma_f32_16x16x16_bf16 v[116:119], v[204:205], v[52:53], v[116:119]
	v_mfma_f32_16x16x16_bf16 v[120:123], v[206:207], v[52:53], v[120:123]
	v_mfma_f32_16x16x16_bf16 v[124:127], v[208:209], v[52:53], v[124:127]
	v_fmac_f32_e32 v156, v98, v98
	v_add_f32_e32 v154, v155, v156
	v_mul_f32_e32 v155, v101, v101
	v_mul_f32_e32 v156, v103, v103
	v_fmac_f32_e32 v155, v100, v100
	v_fmac_f32_e32 v156, v102, v102
	v_add_f32_e32 v155, v155, v156
	v_add_f32_e32 v154, v154, v155
	v_mul_f32_e32 v155, v105, v105
	v_mul_f32_e32 v156, v107, v107
	v_fmac_f32_e32 v155, v104, v104
	v_fmac_f32_e32 v156, v106, v106
	s_waitcnt lgkmcnt(0)
	s_add_i32 s93, s79, 16
	s_mov_b32 m0, s15
	v_add_u32_e32 v164, s93, v162
	v_lshl_or_b32 v164, v164, 7, v220
	global_load_lds_dwordx4 v164, s[30:31]
	s_add_i32 m0, s15, 0x400
	v_add_u32_e32 v165, s93, v163
	v_lshl_or_b32 v165, v165, 7, v221
	global_load_lds_dwordx4 v165, s[30:31]
	s_waitcnt vmcnt(8)
	v_add_u32_e32 v72, s16, v225
	v_add_u32_e32 v73, s16, v226
	v_add_u32_e32 v74, s16, v227
	v_add_u32_e32 v75, s16, v228
	ds_read_b64_tr_b16 v[202:203], v72
	ds_read_b64_tr_b16 v[204:205], v73
	ds_read_b64_tr_b16 v[206:207], v74
	ds_read_b64_tr_b16 v[208:209], v75
	v_mfma_f32_16x16x16_bf16 v[112:115], v[88:89], v[56:57], v[112:115]
	v_mfma_f32_16x16x16_bf16 v[116:119], v[90:91], v[56:57], v[116:119]
	v_mfma_f32_16x16x16_bf16 v[120:123], v[92:93], v[56:57], v[120:123]
	v_mfma_f32_16x16x16_bf16 v[124:127], v[94:95], v[56:57], v[124:127]
	v_add_f32_e32 v155, v155, v156
	v_add_f32_e32 v154, v154, v155
	v_mul_f32_e32 v155, v109, v109
	v_mul_f32_e32 v156, v111, v111
	v_fmac_f32_e32 v155, v108, v108
	v_fmac_f32_e32 v156, v110, v110
	v_add_f32_e32 v155, v155, v156
	v_add_f32_e32 v154, v154, v155
	v_cvt_pk_bf16_f32 v96, v96, v97
	v_cvt_pk_bf16_f32 v97, v98, v99
	v_cvt_pk_bf16_f32 v100, v100, v101
	v_cvt_pk_bf16_f32 v101, v102, v103
	s_waitcnt lgkmcnt(0)
	s_add_i32 s93, s79, 0xffffffc0
	s_mov_b32 m0, s16
	v_add_u32_e32 v164, s93, v162
	v_med3_i32 v164, v164, 0, s41
	v_lshl_or_b32 v164, v164, 7, v220
	global_load_lds_dwordx4 v164, s[34:35]
	s_add_i32 m0, s16, 0x400
	v_add_u32_e32 v165, s93, v163
	v_med3_i32 v165, v165, 0, s41
	v_lshl_or_b32 v165, v165, 7, v221
	global_load_lds_dwordx4 v165, s[34:35]
	s_waitcnt vmcnt(8)
	v_add_u32_e32 v72, s12, v225
	v_add_u32_e32 v73, s12, v226
	v_add_u32_e32 v74, s12, v227
	v_add_u32_e32 v75, s12, v228
	ds_read_b64_tr_b16 v[88:89], v72
	ds_read_b64_tr_b16 v[90:91], v73
	ds_read_b64_tr_b16 v[92:93], v74
	ds_read_b64_tr_b16 v[94:95], v75
	v_mfma_f32_16x16x16_bf16 v[112:115], v[202:203], v[60:61], v[112:115]
	v_mfma_f32_16x16x16_bf16 v[116:119], v[204:205], v[60:61], v[116:119]
	v_mfma_f32_16x16x16_bf16 v[120:123], v[206:207], v[60:61], v[120:123]
	v_mfma_f32_16x16x16_bf16 v[124:127], v[208:209], v[60:61], v[124:127]
	v_cvt_pk_bf16_f32 v104, v104, v105
	v_cvt_pk_bf16_f32 v105, v106, v107
	v_cvt_pk_bf16_f32 v108, v108, v109
	v_cvt_pk_bf16_f32 v109, v110, v111
	v_add_u32_e32 v157, s42, v188
	s_lshl_b32 s90, s43, 7
	v_lshlrev_b32_e32 v158, 11, v157
	v_add3_u32 v158, v158, s90, v233
	v_mov_b32_e32 v76, v96
	v_mov_b32_e32 v77, v97
	v_mov_b32_e32 v78, v100
	v_mov_b32_e32 v79, v101
	s_waitcnt lgkmcnt(0)
	s_add_i32 s93, s79, 0xffffffd0
	s_mov_b32 m0, s12
	v_add_u32_e32 v164, s93, v162
	v_med3_i32 v164, v164, 0, s41
	v_lshl_or_b32 v164, v164, 7, v220
	global_load_lds_dwordx4 v164, s[34:35]
	s_add_i32 m0, s12, 0x400
	v_add_u32_e32 v165, s93, v163
	v_med3_i32 v165, v165, 0, s41
	v_lshl_or_b32 v165, v165, 7, v221
	global_load_lds_dwordx4 v165, s[34:35]
	s_waitcnt vmcnt(8)
	v_add_u32_e32 v72, s13, v225
	v_add_u32_e32 v73, s13, v226
	v_add_u32_e32 v74, s13, v227
	v_add_u32_e32 v75, s13, v228
	ds_read_b64_tr_b16 v[202:203], v72
	ds_read_b64_tr_b16 v[204:205], v73
	ds_read_b64_tr_b16 v[206:207], v74
	ds_read_b64_tr_b16 v[208:209], v75
	v_mfma_f32_16x16x16_bf16 v[112:115], v[88:89], v[64:65], v[112:115]
	v_mfma_f32_16x16x16_bf16 v[116:119], v[90:91], v[64:65], v[116:119]
	v_mfma_f32_16x16x16_bf16 v[120:123], v[92:93], v[64:65], v[120:123]
	v_mfma_f32_16x16x16_bf16 v[124:127], v[94:95], v[64:65], v[124:127]
	s_nop 1
	v_permlane16_swap_b32_e32 v76, v78
	v_permlane16_swap_b32_e32 v77, v79
	v_mov_b32_e32 v80, v104
	v_mov_b32_e32 v81, v105
	v_mov_b32_e32 v82, v108
	v_mov_b32_e32 v83, v109
	s_nop 1
	v_permlane16_swap_b32_e32 v80, v82
	v_permlane16_swap_b32_e32 v81, v83
	v_mov_b32_e32 v155, v154
	s_nop 1
	v_permlane16_swap_b32_e32 v154, v155
	s_waitcnt lgkmcnt(0)
	s_add_i32 s93, s79, 0xffffffe0
	s_mov_b32 m0, s13
	v_add_u32_e32 v164, s93, v162
	v_med3_i32 v164, v164, 0, s41
	v_lshl_or_b32 v164, v164, 7, v220
	global_load_lds_dwordx4 v164, s[34:35]
	s_add_i32 m0, s13, 0x400
	v_add_u32_e32 v165, s93, v163
	v_med3_i32 v165, v165, 0, s41
	v_lshl_or_b32 v165, v165, 7, v221
	global_load_lds_dwordx4 v165, s[34:35]
	v_mfma_f32_16x16x16_bf16 v[112:115], v[202:203], v[68:69], v[112:115]
	v_mfma_f32_16x16x16_bf16 v[116:119], v[204:205], v[68:69], v[116:119]
	v_mfma_f32_16x16x16_bf16 v[120:123], v[206:207], v[68:69], v[120:123]
	v_mfma_f32_16x16x16_bf16 v[124:127], v[208:209], v[68:69], v[124:127]
	v_add_f32_e32 v154, v154, v155
	v_mov_b32_e32 v155, v154
	s_nop 1
	v_permlane32_swap_b32_e32 v154, v155
	v_add_f32_e32 v154, v154, v155
	v_mul_u32_u24_e32 v157, 48, v157
	s_lshl_b32 s90, s43, 2
	v_add_u32_e32 v157, s90, v157
	s_nop 1
	global_store_dwordx4 v158, v[76:79], s[48:49] offset:0
	global_store_dwordx4 v158, v[80:83], s[48:49] offset:64
	s_and_saveexec_b64 s[80:81], s[74:75]
	global_store_dword v157, v154, s[50:51]
	s_mov_b64 exec, s[80:81]
	s_waitcnt lgkmcnt(0)
	v_max_f32_e32 v146, v182, v186
	v_sub_f32_e32 v148, v182, v146
	v_sub_f32_e32 v150, v186, v146
	v_exp_f32_e32 v148, v148
	v_exp_f32_e32 v150, v150
	v_mov_b32_e32 v186, v146
	v_mul_f32_e32 v187, v187, v150
	v_fmac_f32_e32 v187, v183, v148
	v_pk_mul_f32 v[112:113], v[150:151], v[112:113] op_sel_hi:[0,1]
	v_pk_mul_f32 v[114:115], v[150:151], v[114:115] op_sel_hi:[0,1]
	v_pk_mul_f32 v[116:117], v[150:151], v[116:117] op_sel_hi:[0,1]
	v_pk_mul_f32 v[118:119], v[150:151], v[118:119] op_sel_hi:[0,1]
	v_pk_mul_f32 v[120:121], v[150:151], v[120:121] op_sel_hi:[0,1]
	v_pk_mul_f32 v[122:123], v[150:151], v[122:123] op_sel_hi:[0,1]
	v_pk_mul_f32 v[124:125], v[150:151], v[124:125] op_sel_hi:[0,1]
	v_pk_mul_f32 v[126:127], v[150:151], v[126:127] op_sel_hi:[0,1]
	v_pk_fma_f32 v[112:113], v[148:149], v[166:167], v[112:113] op_sel_hi:[0,1,1]
	v_pk_fma_f32 v[114:115], v[148:149], v[168:169], v[114:115] op_sel_hi:[0,1,1]
	v_pk_fma_f32 v[116:117], v[148:149], v[170:171], v[116:117] op_sel_hi:[0,1,1]
	v_pk_fma_f32 v[118:119], v[148:149], v[172:173], v[118:119] op_sel_hi:[0,1,1]
	v_pk_fma_f32 v[120:121], v[148:149], v[174:175], v[120:121] op_sel_hi:[0,1,1]
	v_pk_fma_f32 v[122:123], v[148:149], v[176:177], v[122:123] op_sel_hi:[0,1,1]
	v_pk_fma_f32 v[124:125], v[148:149], v[178:179], v[124:125] op_sel_hi:[0,1,1]
	v_pk_fma_f32 v[126:127], v[148:149], v[180:181], v[126:127] op_sel_hi:[0,1,1]
	v_div_scale_f32 v147, s[94:95], v187, v187, 1.0
	v_rcp_f32_e32 v148, v147
	v_div_scale_f32 v149, vcc, 1.0, v187, 1.0
	v_fma_f32 v150, -v147, v148, 1.0
	v_fmac_f32_e32 v148, v150, v148
	v_mul_f32_e32 v150, v149, v148
	v_fma_f32 v151, -v147, v150, v149
	v_fmac_f32_e32 v150, v151, v148
	v_fma_f32 v147, -v147, v150, v149
	s_nop 1
	v_div_fmas_f32 v147, v147, v148, v150
	v_div_fixup_f32 v152, v147, v187, 1.0
	v_pk_mul_f32 v[112:113], v[152:153], v[112:113] op_sel_hi:[0,1]
	v_pk_mul_f32 v[114:115], v[152:153], v[114:115] op_sel_hi:[0,1]
	v_pk_mul_f32 v[116:117], v[152:153], v[116:117] op_sel_hi:[0,1]
	v_pk_mul_f32 v[118:119], v[152:153], v[118:119] op_sel_hi:[0,1]
	v_pk_mul_f32 v[120:121], v[152:153], v[120:121] op_sel_hi:[0,1]
	v_pk_mul_f32 v[122:123], v[152:153], v[122:123] op_sel_hi:[0,1]
	v_pk_mul_f32 v[124:125], v[152:153], v[124:125] op_sel_hi:[0,1]
	v_pk_mul_f32 v[126:127], v[152:153], v[126:127] op_sel_hi:[0,1]
	v_mul_f32_e32 v155, v113, v113
	v_mul_f32_e32 v156, v115, v115
	v_fmac_f32_e32 v155, v112, v112
	v_fmac_f32_e32 v156, v114, v114
	v_add_f32_e32 v154, v155, v156
	v_mul_f32_e32 v155, v117, v117
	v_mul_f32_e32 v156, v119, v119
	v_fmac_f32_e32 v155, v116, v116
	v_fmac_f32_e32 v156, v118, v118
	v_add_f32_e32 v155, v155, v156
	v_add_f32_e32 v154, v154, v155
	v_mul_f32_e32 v155, v121, v121
	v_mul_f32_e32 v156, v123, v123
	v_fmac_f32_e32 v155, v120, v120
	v_fmac_f32_e32 v156, v122, v122
	v_add_f32_e32 v155, v155, v156
	v_add_f32_e32 v154, v154, v155
	v_mul_f32_e32 v155, v125, v125
	v_mul_f32_e32 v156, v127, v127
	v_fmac_f32_e32 v155, v124, v124
	v_fmac_f32_e32 v156, v126, v126
	v_add_f32_e32 v155, v155, v156
	v_add_f32_e32 v154, v154, v155
	v_cvt_pk_bf16_f32 v112, v112, v113
	v_cvt_pk_bf16_f32 v113, v114, v115
	v_cvt_pk_bf16_f32 v116, v116, v117
	v_cvt_pk_bf16_f32 v117, v118, v119
	v_cvt_pk_bf16_f32 v120, v120, v121
	v_cvt_pk_bf16_f32 v121, v122, v123
	v_cvt_pk_bf16_f32 v124, v124, v125
	v_cvt_pk_bf16_f32 v125, v126, v127
	v_add_u32_e32 v157, s42, v189
	s_lshl_b32 s90, s43, 7
	v_lshlrev_b32_e32 v158, 11, v157
	v_add3_u32 v158, v158, s90, v233
	v_mov_b32_e32 v160, v112
	v_mov_b32_e32 v161, v113
	v_mov_b32_e32 v162, v116
	v_mov_b32_e32 v163, v117
	s_nop 1
	v_permlane16_swap_b32_e32 v160, v162
	v_permlane16_swap_b32_e32 v161, v163
	s_nop 1
	global_store_dwordx4 v158, v[160:163], s[48:49] offset:0
	s_nop 1
	v_mov_b32_e32 v160, v120
	v_mov_b32_e32 v161, v121
	v_mov_b32_e32 v162, v124
	v_mov_b32_e32 v163, v125
	s_nop 1
	v_permlane16_swap_b32_e32 v160, v162
	v_permlane16_swap_b32_e32 v161, v163
	s_nop 1
	global_store_dwordx4 v158, v[160:163], s[48:49] offset:64
	s_nop 1
	v_mov_b32_e32 v155, v154
	s_nop 1
	v_permlane16_swap_b32_e32 v154, v155
	v_add_f32_e32 v154, v154, v155
	v_mov_b32_e32 v155, v154
	s_nop 1
	v_permlane32_swap_b32_e32 v154, v155
	v_add_f32_e32 v154, v154, v155
	v_mul_u32_u24_e32 v157, 48, v157
	s_lshl_b32 s90, s43, 2
	v_add_u32_e32 v157, s90, v157
	s_and_saveexec_b64 s[80:81], s[74:75]
	global_store_dword v157, v154, s[50:51]
	s_mov_b64 exec, s[80:81]
	s_waitcnt lgkmcnt(0)
	s_barrier
	s_mov_b32 s90, s14
	s_mov_b32 s91, s15
	s_mov_b32 s92, s16
	s_mov_b32 s93, s12
	s_mov_b32 s97, s13
	s_mov_b32 s12, s90
	s_mov_b32 s13, s91
	s_mov_b32 s14, s92
	s_mov_b32 s15, s93
	s_mov_b32 s16, s97
	s_mov_b64 s[18:19], s[30:31]
	s_mov_b64 s[20:21], s[34:35]
	s_mov_b64 s[24:25], s[36:37]
	s_mov_b32 s38, s39
	s_mov_b32 s40, s41
	s_mov_b32 s42, s44
	s_mov_b32 s43, s45
	s_mov_b32 s9, 0
	s_add_i32 s11, s11, s66
	s_cmpk_lt_u32 s11, 0x900
	s_cbranch_scc1 .Latt_unit
	v_readlane_b32 s0, v244, 20
	s_bfe_u32 s3, s0, 0x20006
